# FFN-in epilogue: ACT stored as 8 dwordx4 instead of 16 dwordx2 per lane-tile (on v36)
# baseline (speedup 1.0000x reference)
.LBB0_1887:
	s_or_b64 exec, exec, s[42:43]
	v_lshl_or_b32 v212, s40, 7, v194
	v_ashrrev_i32_e32 v213, 31, v212
	v_lshlrev_b64 v[132:133], 2, v[212:213]
	v_lshl_add_u64 v[206:207], s[56:57], 0, v[132:133]
	v_lshl_add_u64 v[208:209], v[130:131], 2, v[196:197]
	v_add_co_u32_e32 v130, vcc, 0x15000, v206
	v_lshl_add_u64 v[210:211], s[58:59], 0, v[132:133]
	s_nop 0
	v_addc_co_u32_e32 v131, vcc, 0, v207, vcc
	v_add_co_u32_e32 v132, vcc, 0x2b000, v206
	s_waitcnt lgkmcnt(0)
	s_barrier
	v_mov_b32_e32 v140, 0
	v_addc_co_u32_e32 v133, vcc, 0, v207, vcc
	v_mov_b32_e32 v134, s94
	v_mov_b32_e32 v136, v224
	v_mov_b32_e32 v137, v225
	v_mov_b32_e32 v138, v226
	v_mov_b32_e32 v139, v227
	s_nop 0
	s_nop 0
	s_nop 0
	v_add_co_u32_e32 v130, vcc, 0xa000, v210
	v_mov_b32_e32 v146, 0
	s_nop 0
	v_addc_co_u32_e32 v131, vcc, 0, v211, vcc
	v_add_co_u32_e32 v142, vcc, 0xa000, v206
	v_mov_b32_e32 v130, v228
	v_mov_b32_e32 v131, v229
	v_mov_b32_e32 v132, v230
	v_mov_b32_e32 v133, v231
	s_nop 0
	s_nop 0
	s_nop 0
	v_addc_co_u32_e32 v143, vcc, 0, v207, vcc
	v_add_co_u32_e32 v144, vcc, 0x20000, v206
	v_mov_b32_e32 v147, 0
	s_nop 0
	v_addc_co_u32_e32 v145, vcc, 0, v207, vcc
	s_nop 0
	s_nop 0
	v_add_co_u32_e32 v142, vcc, 0x35000, v206
	v_mov_b32_e32 v144, 0
	s_nop 0
	v_addc_co_u32_e32 v143, vcc, 0, v207, vcc
	s_nop 0
	v_mov_b32_e32 v145, 0
	s_and_saveexec_b64 s[40:41], s[26:27]
	ds_read_b128 v[144:147], v215
	s_or_b64 exec, exec, s[40:41]
	v_mov_b32_e32 v141, 0
	v_mov_b32_e32 v142, 0
	v_mov_b32_e32 v143, 0
	s_and_saveexec_b64 s[40:41], s[26:27]
	ds_read_b128 v[140:143], v215 offset:512
	s_or_b64 exec, exec, s[40:41]
	s_nop 0
	v_pk_mul_f32 v[176:177], v[176:177], v[134:135] op_sel_hi:[1,0]
	v_pk_mul_f32 v[178:179], v[178:179], v[134:135] op_sel_hi:[1,0]
	v_pk_mul_f32 v[226:227], v[148:149], v[176:177]
	v_pk_mul_f32 v[230:231], v[176:177], v[156:157]
	v_pk_mul_f32 v[176:177], v[176:177], v[152:153]
	v_pk_mul_f32 v[152:153], v[134:135], v[162:163] op_sel_hi:[0,1]
	v_pk_mul_f32 v[134:135], v[134:135], v[160:161] op_sel_hi:[0,1]
	v_pk_mul_f32 v[224:225], v[150:151], v[178:179]
	v_pk_mul_f32 v[228:229], v[178:179], v[158:159]
	v_pk_mul_f32 v[178:179], v[178:179], v[154:155]
	v_pk_mul_f32 v[154:155], v[168:169], v[134:135]
	v_pk_mul_f32 v[156:157], v[134:135], v[164:165]
	v_pk_mul_f32 v[158:159], v[134:135], v[172:173]
	s_waitcnt lgkmcnt(0)
	v_mov_b32_dpp v160, v144 row_ror:1 row_mask:0xf bank_mask:0xf
	v_mov_b32_dpp v161, v144 row_ror:2 row_mask:0xf bank_mask:0xf
	v_mov_b32_dpp v168, v145 row_ror:1 row_mask:0xf bank_mask:0xf
	v_mov_b32_dpp v169, v145 row_ror:2 row_mask:0xf bank_mask:0xf
	v_mov_b32_dpp v135, v126 row_ror:1 row_mask:0xf bank_mask:0xf
	v_mov_b32_dpp v172, v126 row_ror:2 row_mask:0xf bank_mask:0xf
	v_mov_b32_dpp v238, v122 row_ror:1 row_mask:0xf bank_mask:0xf
	v_mov_b32_dpp v144, v140 row_ror:1 row_mask:0xf bank_mask:0xf
	v_mov_b32_dpp v239, v122 row_ror:2 row_mask:0xf bank_mask:0xf
	v_mov_b32_dpp v145, v140 row_ror:2 row_mask:0xf bank_mask:0xf
	v_mov_b32_dpp v223, v146 row_ror:1 row_mask:0xf bank_mask:0xf
	v_mov_b32_dpp v233, v146 row_ror:2 row_mask:0xf bank_mask:0xf
	v_mov_b32_dpp v235, v147 row_ror:1 row_mask:0xf bank_mask:0xf
	v_mov_b32_dpp v237, v147 row_ror:2 row_mask:0xf bank_mask:0xf
	v_cndmask_b32_e64 v163, v238, v144, s[8:9]
	v_cndmask_b32_e64 v162, v135, v160, s[8:9]
	v_cndmask_b32_e64 v165, v239, v145, s[6:7]
	v_cndmask_b32_e64 v164, v172, v161, s[6:7]
	v_mov_b32_e32 v160, v126
	v_mov_b32_e32 v161, v122
	v_mov_b32_e32 v144, v176
	v_mov_b32_e32 v145, v158
	v_mov_b32_e32 v146, v136
	v_mov_b32_e32 v147, v130
	v_pk_mul_f32 v[150:151], v[152:153], v[166:167]
	v_pk_fma_f32 v[166:167], v[160:161], v[144:145], v[146:147]
	v_mov_b32_e32 v160, v230
	v_mov_b32_e32 v161, v156
	v_mov_b32_dpp v176, v123 row_ror:1 row_mask:0xf bank_mask:0xf
	v_mov_b32_dpp v122, v141 row_ror:1 row_mask:0xf bank_mask:0xf
	v_pk_mul_f32 v[148:149], v[170:171], v[152:153]
	v_pk_mul_f32 v[152:153], v[152:153], v[174:175]
	v_mov_b32_dpp v173, v127 row_ror:1 row_mask:0xf bank_mask:0xf
	v_pk_fma_f32 v[166:167], v[160:161], v[162:163], v[166:167]
	v_mov_b32_e32 v162, v226
	v_mov_b32_dpp v126, v141 row_ror:2 row_mask:0xf bank_mask:0xf
	v_cndmask_b32_e64 v141, v176, v122, s[8:9]
	v_mov_b32_e32 v122, v127
	v_mov_b32_e32 v158, v177
	v_mov_b32_e32 v130, v137
	v_mov_b32_dpp v174, v127 row_ror:2 row_mask:0xf bank_mask:0xf
	v_mov_b32_e32 v163, v154
	v_mov_b32_dpp v226, v123 row_ror:2 row_mask:0xf bank_mask:0xf
	v_cndmask_b32_e64 v140, v173, v168, s[8:9]
	v_pk_fma_f32 v[122:123], v[122:123], v[158:159], v[130:131]
	v_mov_b32_e32 v156, v231
	v_pk_fma_f32 v[170:171], v[162:163], v[164:165], v[166:167]
	v_cndmask_b32_e64 v165, v226, v126, s[6:7]
	v_cndmask_b32_e64 v164, v174, v169, s[6:7]
	v_pk_fma_f32 v[122:123], v[156:157], v[140:141], v[122:123]
	v_mov_b32_e32 v154, v227
	v_mov_b32_dpp v175, v128 row_ror:1 row_mask:0xf bank_mask:0xf
	v_pk_fma_f32 v[122:123], v[154:155], v[164:165], v[122:123]
	v_mov_b32_dpp v177, v124 row_ror:1 row_mask:0xf bank_mask:0xf
	v_mov_b32_dpp v126, v142 row_ror:1 row_mask:0xf bank_mask:0xf
	v_mov_b32_e32 v166, v128
	v_mov_b32_e32 v167, v124
	v_mov_b32_e32 v140, v178
	v_mov_b32_e32 v141, v152
	v_mov_b32_e32 v164, v138
	v_mov_b32_e32 v165, v132
	v_mov_b32_dpp v232, v128 row_ror:2 row_mask:0xf bank_mask:0xf
	v_mov_b32_dpp v227, v124 row_ror:2 row_mask:0xf bank_mask:0xf
	v_mov_b32_dpp v136, v142 row_ror:2 row_mask:0xf bank_mask:0xf
	v_cndmask_b32_e64 v127, v177, v126, s[8:9]
	v_cndmask_b32_e64 v126, v175, v223, s[8:9]
	v_pk_fma_f32 v[168:169], v[166:167], v[140:141], v[164:165]
	v_mov_b32_e32 v166, v228
	v_mov_b32_e32 v167, v150
	v_cndmask_b32_e64 v137, v227, v136, s[6:7]
	v_cndmask_b32_e64 v136, v232, v233, s[6:7]
	v_pk_fma_f32 v[126:127], v[166:167], v[126:127], v[168:169]
	v_mov_b32_e32 v168, v224
	v_mov_b32_e32 v169, v148
	v_mov_b32_dpp v178, v125 row_ror:1 row_mask:0xf bank_mask:0xf
	v_mov_b32_dpp v124, v143 row_ror:1 row_mask:0xf bank_mask:0xf
	v_mov_b32_dpp v234, v129 row_ror:1 row_mask:0xf bank_mask:0xf
	v_mov_b32_dpp v236, v129 row_ror:2 row_mask:0xf bank_mask:0xf
	v_pk_fma_f32 v[126:127], v[168:169], v[136:137], v[126:127]
	v_cndmask_b32_e64 v137, v178, v124, s[8:9]
	v_mov_b32_e32 v124, v129
	v_mul_f32_e32 v129, 0xbfb8aa3b, v122
	v_mov_b32_e32 v152, v179
	v_mov_b32_e32 v132, v139
	v_exp_f32_e32 v129, v129
	v_mov_b32_dpp v223, v125 row_ror:2 row_mask:0xf bank_mask:0xf
	v_mov_b32_dpp v128, v143 row_ror:2 row_mask:0xf bank_mask:0xf
	v_cndmask_b32_e64 v136, v234, v235, s[8:9]
	v_pk_fma_f32 v[124:125], v[124:125], v[152:153], v[132:133]
	v_mov_b32_e32 v150, v229
	v_cndmask_b32_e64 v143, v223, v128, s[6:7]
	v_cndmask_b32_e64 v142, v236, v237, s[6:7]
	v_pk_fma_f32 v[124:125], v[150:151], v[136:137], v[124:125]
	v_mov_b32_e32 v148, v225
	v_pk_fma_f32 v[124:125], v[148:149], v[142:143], v[124:125]
	v_add_f32_e32 v129, 1.0, v129
	v_mul_f32_e32 v136, 0xbfb8aa3b, v126
	v_mul_f32_e32 v137, 0xbfb8aa3b, v124
	v_mul_f32_e32 v128, 0xbfb8aa3b, v170
	v_rcp_f32_e32 v129, v129
	v_exp_f32_e32 v136, v136
	v_exp_f32_e32 v137, v137
	v_exp_f32_e32 v128, v128
	v_mul_f32_e32 v122, v122, v129
	v_add_f32_e32 v129, 1.0, v136
	v_add_f32_e32 v136, 1.0, v137
	v_add_f32_e32 v128, 1.0, v128
	v_rcp_f32_e32 v136, v136
	v_rcp_f32_e32 v128, v128
	v_rcp_f32_e32 v129, v129
	v_mul_f32_e32 v122, v122, v123
	v_mul_f32_e32 v124, v124, v136
	v_mul_f32_e32 v128, v170, v128
	v_mul_f32_e32 v123, v126, v129
	v_mul_f32_e32 v124, v124, v125
	v_lshl_add_u32 v188, s38, 8, v1
	v_mul_f32_e32 v128, v128, v171
	v_mul_f32_e32 v123, v123, v127
	v_cvt_pk_bf16_f32 v126, v128, v122
	v_cvt_pk_bf16_f32 v127, v123, v124
	v_mov_b64_e32 v[124:125], s[12:13]
	v_mad_i64_i32 v[122:123], s[38:39], v188, s72, v[124:125]
	v_lshlrev_b64 v[138:139], 1, v[212:213]
	v_lshl_add_u64 v[122:123], v[122:123], 0, v[138:139]
	v_mov_b32_dpp v142, v118 row_ror:1 row_mask:0xf bank_mask:0xf
	v_mov_b32_dpp v225, v114 row_ror:1 row_mask:0xf bank_mask:0xf
	v_mov_b32_e32 v136, v118
	v_mov_b32_e32 v137, v114
	v_mov_b32_e32 v240, v126
	v_mov_b32_e32 v241, v127
	v_mov_b32_dpp v143, v118 row_ror:2 row_mask:0xf bank_mask:0xf
	v_mov_b32_dpp v228, v114 row_ror:2 row_mask:0xf bank_mask:0xf
	v_cndmask_b32_e64 v127, v225, v238, s[8:9]
	v_cndmask_b32_e64 v126, v142, v135, s[8:9]
	v_pk_fma_f32 v[136:137], v[136:137], v[144:145], v[146:147]
	v_mov_b32_dpp v170, v119 row_ror:1 row_mask:0xf bank_mask:0xf
	v_cndmask_b32_e64 v129, v228, v239, s[6:7]
	v_cndmask_b32_e64 v128, v143, v172, s[6:7]
	v_pk_fma_f32 v[126:127], v[160:161], v[126:127], v[136:137]
	v_mov_b32_dpp v135, v115 row_ror:1 row_mask:0xf bank_mask:0xf
	v_mov_b32_e32 v114, v119
	v_mov_b32_dpp v171, v119 row_ror:2 row_mask:0xf bank_mask:0xf
	v_pk_fma_f32 v[126:127], v[162:163], v[128:129], v[126:127]
	v_mov_b32_dpp v172, v115 row_ror:2 row_mask:0xf bank_mask:0xf
	v_cndmask_b32_e64 v129, v135, v176, s[8:9]
	v_cndmask_b32_e64 v128, v170, v173, s[8:9]
	v_pk_fma_f32 v[114:115], v[114:115], v[158:159], v[130:131]
	v_cndmask_b32_e64 v137, v172, v226, s[6:7]
	v_cndmask_b32_e64 v136, v171, v174, s[6:7]
	v_pk_fma_f32 v[114:115], v[156:157], v[128:129], v[114:115]
	v_pk_fma_f32 v[114:115], v[154:155], v[136:137], v[114:115]
	v_mov_b32_dpp v173, v116 row_ror:1 row_mask:0xf bank_mask:0xf
	v_mov_b32_dpp v174, v116 row_ror:2 row_mask:0xf bank_mask:0xf
	v_mov_b32_e32 v137, v116
	v_mul_f32_e32 v116, 0xbfb8aa3b, v126
	v_mov_b32_dpp v179, v120 row_ror:1 row_mask:0xf bank_mask:0xf
	v_mov_b32_dpp v212, v120 row_ror:2 row_mask:0xf bank_mask:0xf
	v_mov_b32_e32 v136, v120
	v_exp_f32_e32 v120, v116
	v_cndmask_b32_e64 v119, v173, v177, s[8:9]
	v_add_f32_e32 v120, 1.0, v120
	v_mov_b32_dpp v213, v121 row_ror:1 row_mask:0xf bank_mask:0xf
	v_mov_b32_dpp v224, v121 row_ror:2 row_mask:0xf bank_mask:0xf
	v_cndmask_b32_e64 v118, v179, v175, s[8:9]
	v_pk_fma_f32 v[136:137], v[136:137], v[140:141], v[164:165]
	v_mov_b32_e32 v116, v121
	v_rcp_f32_e32 v120, v120
	v_mul_f32_e32 v121, 0xbfb8aa3b, v114
	v_cndmask_b32_e64 v129, v174, v227, s[6:7]
	v_cndmask_b32_e64 v128, v212, v232, s[6:7]
	v_pk_fma_f32 v[118:119], v[166:167], v[118:119], v[136:137]
	v_mov_b32_dpp v175, v117 row_ror:1 row_mask:0xf bank_mask:0xf
	v_exp_f32_e32 v121, v121
	v_pk_fma_f32 v[118:119], v[168:169], v[128:129], v[118:119]
	v_mov_b32_dpp v176, v117 row_ror:2 row_mask:0xf bank_mask:0xf
	v_cndmask_b32_e64 v129, v175, v178, s[8:9]
	v_cndmask_b32_e64 v128, v213, v234, s[8:9]
	v_pk_fma_f32 v[116:117], v[116:117], v[152:153], v[132:133]
	v_cndmask_b32_e64 v137, v176, v223, s[6:7]
	v_cndmask_b32_e64 v136, v224, v236, s[6:7]
	v_pk_fma_f32 v[116:117], v[150:151], v[128:129], v[116:117]
	v_mul_f32_e32 v120, v126, v120
	v_pk_fma_f32 v[116:117], v[148:149], v[136:137], v[116:117]
	v_mul_f32_e32 v120, v120, v127
	v_add_f32_e32 v121, 1.0, v121
	v_mul_f32_e32 v126, 0xbfb8aa3b, v118
	v_mul_f32_e32 v127, 0xbfb8aa3b, v116
	v_rcp_f32_e32 v121, v121
	v_exp_f32_e32 v126, v126
	v_exp_f32_e32 v127, v127
	v_mul_f32_e32 v114, v114, v121
	v_add_f32_e32 v121, 1.0, v126
	v_add_f32_e32 v126, 1.0, v127
	v_rcp_f32_e32 v121, v121
	v_rcp_f32_e32 v126, v126
	v_mul_f32_e32 v114, v114, v115
	v_cvt_pk_bf16_f32 v114, v120, v114
	v_mul_f32_e32 v115, v118, v121
	v_mul_f32_e32 v116, v116, v126
	v_mul_f32_e32 v115, v115, v119
	v_mul_f32_e32 v116, v116, v117
	v_or_b32_e32 v117, 16, v188
	v_cvt_pk_bf16_f32 v115, v115, v116
	v_mad_i64_i32 v[116:117], s[38:39], v117, s72, v[124:125]
	v_lshl_add_u64 v[118:119], v[116:117], 0, v[138:139]
	v_mov_b32_dpp v126, v110 row_ror:1 row_mask:0xf bank_mask:0xf
	v_mov_b32_dpp v223, v106 row_ror:1 row_mask:0xf bank_mask:0xf
	v_mov_b32_e32 v120, v110
	v_mov_b32_e32 v121, v106
	v_mov_b32_e32 v242, v114
	v_mov_b32_e32 v243, v115
	v_mov_b32_dpp v127, v110 row_ror:2 row_mask:0xf bank_mask:0xf
	v_mov_b32_dpp v226, v106 row_ror:2 row_mask:0xf bank_mask:0xf
	v_cndmask_b32_e64 v115, v223, v225, s[8:9]
	v_cndmask_b32_e64 v114, v126, v142, s[8:9]
	v_pk_fma_f32 v[120:121], v[120:121], v[144:145], v[146:147]
	v_mov_b32_dpp v128, v111 row_ror:1 row_mask:0xf bank_mask:0xf
	v_cndmask_b32_e64 v117, v226, v228, s[6:7]
	v_cndmask_b32_e64 v116, v127, v143, s[6:7]
	v_pk_fma_f32 v[114:115], v[160:161], v[114:115], v[120:121]
	v_mov_b32_dpp v142, v107 row_ror:1 row_mask:0xf bank_mask:0xf
	v_mov_b32_e32 v106, v111
	v_mov_b32_dpp v129, v111 row_ror:2 row_mask:0xf bank_mask:0xf
	v_pk_fma_f32 v[114:115], v[162:163], v[116:117], v[114:115]
	v_mov_b32_dpp v143, v107 row_ror:2 row_mask:0xf bank_mask:0xf
	v_cndmask_b32_e64 v117, v142, v135, s[8:9]
	v_cndmask_b32_e64 v116, v128, v170, s[8:9]
	v_pk_fma_f32 v[106:107], v[106:107], v[158:159], v[130:131]
	v_cndmask_b32_e64 v121, v143, v172, s[6:7]
	v_cndmask_b32_e64 v120, v129, v171, s[6:7]
	v_pk_fma_f32 v[106:107], v[156:157], v[116:117], v[106:107]
	v_pk_fma_f32 v[106:107], v[154:155], v[120:121], v[106:107]
	v_mov_b32_dpp v135, v108 row_ror:1 row_mask:0xf bank_mask:0xf
	v_mov_b32_dpp v170, v108 row_ror:2 row_mask:0xf bank_mask:0xf
	v_mov_b32_e32 v121, v108
	v_mul_f32_e32 v108, 0xbfb8aa3b, v114
	v_exp_f32_e32 v172, v108
	v_mov_b32_dpp v136, v112 row_ror:1 row_mask:0xf bank_mask:0xf
	v_mov_b32_e32 v120, v112
	v_mov_b32_dpp v137, v112 row_ror:2 row_mask:0xf bank_mask:0xf
	v_cndmask_b32_e64 v111, v135, v173, s[8:9]
	v_cndmask_b32_e64 v110, v136, v179, s[8:9]
	v_pk_fma_f32 v[120:121], v[120:121], v[140:141], v[164:165]
	v_mov_b32_dpp v177, v113 row_ror:1 row_mask:0xf bank_mask:0xf
	v_cndmask_b32_e64 v117, v170, v174, s[6:7]
	v_cndmask_b32_e64 v116, v137, v212, s[6:7]
	v_pk_fma_f32 v[110:111], v[166:167], v[110:111], v[120:121]
	v_mov_b32_dpp v112, v109 row_ror:1 row_mask:0xf bank_mask:0xf
	v_mov_b32_e32 v108, v113
	v_mov_b32_dpp v178, v113 row_ror:2 row_mask:0xf bank_mask:0xf
	v_pk_fma_f32 v[110:111], v[168:169], v[116:117], v[110:111]
	v_mov_b32_dpp v171, v109 row_ror:2 row_mask:0xf bank_mask:0xf
	v_cndmask_b32_e64 v117, v112, v175, s[8:9]
	v_cndmask_b32_e64 v116, v177, v213, s[8:9]
	v_pk_fma_f32 v[108:109], v[108:109], v[152:153], v[132:133]
	v_add_f32_e32 v113, 1.0, v172
	v_pk_fma_f32 v[108:109], v[150:151], v[116:117], v[108:109]
	v_rcp_f32_e32 v113, v113
	v_mul_f32_e32 v116, 0xbfb8aa3b, v106
	v_exp_f32_e32 v116, v116
	v_cndmask_b32_e64 v121, v171, v176, s[6:7]
	v_cndmask_b32_e64 v120, v178, v224, s[6:7]
	v_pk_fma_f32 v[108:109], v[148:149], v[120:121], v[108:109]
	v_mul_f32_e32 v113, v114, v113
	v_mul_f32_e32 v113, v113, v115
	v_add_f32_e32 v114, 1.0, v116
	v_mul_f32_e32 v115, 0xbfb8aa3b, v110
	v_mul_f32_e32 v116, 0xbfb8aa3b, v108
	v_rcp_f32_e32 v114, v114
	v_exp_f32_e32 v115, v115
	v_exp_f32_e32 v116, v116
	v_mul_f32_e32 v106, v106, v114
	v_add_f32_e32 v114, 1.0, v115
	v_add_f32_e32 v115, 1.0, v116
	v_rcp_f32_e32 v114, v114
	v_rcp_f32_e32 v115, v115
	v_mul_f32_e32 v106, v106, v107
	v_cvt_pk_bf16_f32 v106, v113, v106
	v_mul_f32_e32 v107, v110, v114
	v_mul_f32_e32 v108, v108, v115
	v_mul_f32_e32 v107, v107, v111
	v_mul_f32_e32 v108, v108, v109
	v_or_b32_e32 v109, 32, v188
	v_cvt_pk_bf16_f32 v107, v107, v108
	v_mad_i64_i32 v[108:109], s[38:39], v109, s72, v[124:125]
	v_lshl_add_u64 v[120:121], v[108:109], 0, v[138:139]
	v_mov_b32_e32 v244, v106
	v_mov_b32_e32 v245, v107
	v_mov_b32_dpp v106, v102 row_ror:1 row_mask:0xf bank_mask:0xf
	v_mov_b32_dpp v107, v98 row_ror:1 row_mask:0xf bank_mask:0xf
	v_mov_b32_e32 v110, v102
	v_mov_b32_e32 v111, v98
	v_mov_b32_dpp v108, v102 row_ror:2 row_mask:0xf bank_mask:0xf
	v_mov_b32_dpp v109, v98 row_ror:2 row_mask:0xf bank_mask:0xf
	v_cndmask_b32_e64 v107, v107, v223, s[8:9]
	v_cndmask_b32_e64 v106, v106, v126, s[8:9]
	v_pk_fma_f32 v[110:111], v[110:111], v[144:145], v[146:147]
	v_cndmask_b32_e64 v109, v109, v226, s[6:7]
	v_cndmask_b32_e64 v108, v108, v127, s[6:7]
	v_pk_fma_f32 v[106:107], v[160:161], v[106:107], v[110:111]
	v_mov_b32_dpp v98, v99 row_ror:1 row_mask:0xf bank_mask:0xf
	v_mov_b32_dpp v113, v103 row_ror:1 row_mask:0xf bank_mask:0xf
	v_pk_fma_f32 v[106:107], v[162:163], v[108:109], v[106:107]
	v_cndmask_b32_e64 v109, v98, v142, s[8:9]
	v_mov_b32_e32 v98, v103
	v_mov_b32_dpp v114, v103 row_ror:2 row_mask:0xf bank_mask:0xf
	v_mov_b32_dpp v102, v99 row_ror:2 row_mask:0xf bank_mask:0xf
	v_cndmask_b32_e64 v108, v113, v128, s[8:9]
	v_pk_fma_f32 v[98:99], v[98:99], v[158:159], v[130:131]
	v_cndmask_b32_e64 v111, v102, v143, s[6:7]
	v_cndmask_b32_e64 v110, v114, v129, s[6:7]
	v_pk_fma_f32 v[98:99], v[156:157], v[108:109], v[98:99]
	v_mov_b32_dpp v115, v104 row_ror:1 row_mask:0xf bank_mask:0xf
	v_pk_fma_f32 v[98:99], v[154:155], v[110:111], v[98:99]
	v_mov_b32_dpp v102, v100 row_ror:1 row_mask:0xf bank_mask:0xf
	v_mov_b32_e32 v110, v104
	v_mov_b32_e32 v111, v100
	v_mov_b32_dpp v116, v104 row_ror:2 row_mask:0xf bank_mask:0xf
	v_mov_b32_dpp v108, v100 row_ror:2 row_mask:0xf bank_mask:0xf
	v_cndmask_b32_e64 v103, v102, v135, s[8:9]
	v_cndmask_b32_e64 v102, v115, v136, s[8:9]
	v_pk_fma_f32 v[110:111], v[110:111], v[140:141], v[164:165]
	v_cndmask_b32_e64 v109, v108, v170, s[6:7]
	v_cndmask_b32_e64 v108, v116, v137, s[6:7]
	v_pk_fma_f32 v[102:103], v[166:167], v[102:103], v[110:111]
	v_mov_b32_dpp v100, v101 row_ror:1 row_mask:0xf bank_mask:0xf
	v_pk_fma_f32 v[102:103], v[168:169], v[108:109], v[102:103]
	v_cndmask_b32_e64 v109, v100, v112, s[8:9]
	v_mov_b32_dpp v104, v101 row_ror:2 row_mask:0xf bank_mask:0xf
	v_mul_f32_e32 v100, 0xbfb8aa3b, v106
	v_cndmask_b32_e64 v111, v104, v171, s[6:7]
	v_exp_f32_e32 v104, v100
	v_mov_b32_dpp v117, v105 row_ror:1 row_mask:0xf bank_mask:0xf
	v_mov_b32_e32 v100, v105
	v_add_f32_e32 v104, 1.0, v104
	v_mov_b32_dpp v172, v105 row_ror:2 row_mask:0xf bank_mask:0xf
	v_rcp_f32_e32 v104, v104
	v_mul_f32_e32 v105, 0xbfb8aa3b, v98
	v_exp_f32_e32 v105, v105
	v_cndmask_b32_e64 v108, v117, v177, s[8:9]
	v_pk_fma_f32 v[100:101], v[100:101], v[152:153], v[132:133]
	v_cndmask_b32_e64 v110, v172, v178, s[6:7]
	v_pk_fma_f32 v[100:101], v[150:151], v[108:109], v[100:101]
	v_mul_f32_e32 v104, v106, v104
	v_pk_fma_f32 v[100:101], v[148:149], v[110:111], v[100:101]
	v_mul_f32_e32 v104, v104, v107
	v_add_f32_e32 v105, 1.0, v105
	v_mul_f32_e32 v106, 0xbfb8aa3b, v102
	v_mul_f32_e32 v107, 0xbfb8aa3b, v100
	v_rcp_f32_e32 v105, v105
	v_exp_f32_e32 v106, v106
	v_exp_f32_e32 v107, v107
	v_mov_b32_e32 v134, 0
	v_mul_f32_e32 v98, v98, v105
	v_add_f32_e32 v105, 1.0, v106
	v_add_f32_e32 v106, 1.0, v107
	v_rcp_f32_e32 v105, v105
	v_rcp_f32_e32 v106, v106
	v_mul_f32_e32 v98, v98, v99
	v_cvt_pk_bf16_f32 v98, v104, v98
	v_mul_f32_e32 v99, v102, v105
	v_mul_f32_e32 v100, v100, v106
	v_mul_f32_e32 v99, v99, v103
	v_mul_f32_e32 v100, v100, v101
	v_or_b32_e32 v101, 48, v188
	v_cvt_pk_bf16_f32 v99, v99, v100
	v_mad_i64_i32 v[100:101], s[38:39], v101, s72, v[124:125]
	v_lshl_add_u64 v[124:125], v[100:101], 0, v[138:139]
	v_mov_b32_e32 v246, v98
	v_mov_b32_e32 v247, v99
	v_mov_b32_e32 v100, 0
	v_mov_b32_e32 v101, 0
	v_mov_b32_e32 v102, 0
	v_mov_b32_e32 v103, 0
	s_and_saveexec_b64 s[38:39], s[4:5]
	ds_read_b128 v[100:103], v216
	s_or_b64 exec, exec, s[38:39]
	v_mov_b32_e32 v135, 0
	v_mov_b32_e32 v136, 0
	v_mov_b32_e32 v137, 0
	s_and_saveexec_b64 s[38:39], s[4:5]
	ds_read_b128 v[134:137], v216 offset:512
	s_or_b64 exec, exec, s[38:39]
	s_waitcnt lgkmcnt(0)
	v_mov_b32_dpp v116, v102 row_ror:1 row_mask:0xf bank_mask:0xf
	v_mov_b32_dpp v126, v102 row_ror:2 row_mask:0xf bank_mask:0xf
	v_mov_b32_dpp v108, v94 row_ror:1 row_mask:0xf bank_mask:0xf
	v_mov_b32_dpp v106, v100 row_ror:1 row_mask:0xf bank_mask:0xf
	v_mov_b32_e32 v104, v94
	v_mov_b32_e32 v105, v90
	v_mov_b32_dpp v143, v90 row_ror:1 row_mask:0xf bank_mask:0xf
	v_mov_b32_dpp v102, v134 row_ror:1 row_mask:0xf bank_mask:0xf
	v_mov_b32_dpp v170, v90 row_ror:2 row_mask:0xf bank_mask:0xf
	v_mov_b32_dpp v109, v94 row_ror:2 row_mask:0xf bank_mask:0xf
	v_mov_b32_dpp v110, v100 row_ror:2 row_mask:0xf bank_mask:0xf
	v_mov_b32_dpp v128, v103 row_ror:1 row_mask:0xf bank_mask:0xf
	v_mov_b32_dpp v142, v103 row_ror:2 row_mask:0xf bank_mask:0xf
	v_mov_b32_dpp v90, v134 row_ror:2 row_mask:0xf bank_mask:0xf
	v_cndmask_b32_e64 v103, v143, v102, s[8:9]
	v_cndmask_b32_e64 v102, v108, v106, s[8:9]
	v_pk_fma_f32 v[104:105], v[104:105], v[144:145], v[146:147]
	v_cndmask_b32_e64 v107, v170, v90, s[6:7]
	v_cndmask_b32_e64 v106, v109, v110, s[6:7]
	v_pk_fma_f32 v[102:103], v[160:161], v[102:103], v[104:105]
	v_pk_fma_f32 v[102:103], v[162:163], v[106:107], v[102:103]
	v_mov_b32_dpp v111, v95 row_ror:1 row_mask:0xf bank_mask:0xf
	v_mov_b32_dpp v112, v101 row_ror:1 row_mask:0xf bank_mask:0xf
	v_mov_b32_dpp v113, v95 row_ror:2 row_mask:0xf bank_mask:0xf
	v_mov_b32_e32 v94, v95
	v_mov_b32_e32 v95, v91
	v_mov_b32_dpp v106, v91 row_ror:1 row_mask:0xf bank_mask:0xf
	v_mov_b32_dpp v90, v135 row_ror:1 row_mask:0xf bank_mask:0xf
	v_pk_fma_f32 v[94:95], v[94:95], v[158:159], v[130:131]
	v_mov_b32_dpp v107, v91 row_ror:2 row_mask:0xf bank_mask:0xf
	v_cndmask_b32_e64 v91, v106, v90, s[8:9]
	v_cndmask_b32_e64 v90, v111, v112, s[8:9]
	v_pk_fma_f32 v[90:91], v[156:157], v[90:91], v[94:95]
	v_mov_b32_dpp v114, v101 row_ror:2 row_mask:0xf bank_mask:0xf
	v_mov_b32_dpp v115, v96 row_ror:1 row_mask:0xf bank_mask:0xf
	v_mov_b32_e32 v100, v96
	v_mov_b32_e32 v101, v92
	v_mov_b32_dpp v104, v135 row_ror:2 row_mask:0xf bank_mask:0xf
	v_mov_b32_dpp v110, v92 row_ror:1 row_mask:0xf bank_mask:0xf
	v_mov_b32_dpp v94, v136 row_ror:1 row_mask:0xf bank_mask:0xf
	v_mov_b32_dpp v112, v92 row_ror:2 row_mask:0xf bank_mask:0xf
	v_mov_b32_dpp v117, v96 row_ror:2 row_mask:0xf bank_mask:0xf
	v_cndmask_b32_e64 v105, v107, v104, s[6:7]
	v_cndmask_b32_e64 v104, v113, v114, s[6:7]
	v_mov_b32_dpp v92, v136 row_ror:2 row_mask:0xf bank_mask:0xf
	v_cndmask_b32_e64 v95, v110, v94, s[8:9]
	v_cndmask_b32_e64 v94, v115, v116, s[8:9]
	v_pk_fma_f32 v[100:101], v[100:101], v[140:141], v[164:165]
	v_pk_fma_f32 v[90:91], v[154:155], v[104:105], v[90:91]
	v_cndmask_b32_e64 v105, v112, v92, s[6:7]
	v_cndmask_b32_e64 v104, v117, v126, s[6:7]
	v_pk_fma_f32 v[94:95], v[166:167], v[94:95], v[100:101]
	v_pk_fma_f32 v[94:95], v[168:169], v[104:105], v[94:95]
	v_mov_b32_dpp v127, v97 row_ror:1 row_mask:0xf bank_mask:0xf
	v_mov_b32_dpp v129, v97 row_ror:2 row_mask:0xf bank_mask:0xf
	v_mov_b32_e32 v96, v97
	v_mov_b32_e32 v97, v93
	v_mov_b32_dpp v104, v93 row_ror:1 row_mask:0xf bank_mask:0xf
	v_mov_b32_dpp v92, v137 row_ror:1 row_mask:0xf bank_mask:0xf
	v_pk_fma_f32 v[96:97], v[96:97], v[152:153], v[132:133]
	v_mov_b32_dpp v105, v93 row_ror:2 row_mask:0xf bank_mask:0xf
	v_cndmask_b32_e64 v93, v104, v92, s[8:9]
	v_cndmask_b32_e64 v92, v127, v128, s[8:9]
	v_pk_fma_f32 v[92:93], v[150:151], v[92:93], v[96:97]
	v_mul_f32_e32 v97, 0xbfb8aa3b, v90
	v_mov_b32_dpp v100, v137 row_ror:2 row_mask:0xf bank_mask:0xf
	v_exp_f32_e32 v97, v97
	v_cndmask_b32_e64 v101, v105, v100, s[6:7]
	v_mul_f32_e32 v100, 0xbfb8aa3b, v102
	v_exp_f32_e32 v114, v100
	v_cndmask_b32_e64 v100, v129, v142, s[6:7]
	v_pk_fma_f32 v[92:93], v[148:149], v[100:101], v[92:93]
	v_add_f32_e32 v97, 1.0, v97
	v_mul_f32_e32 v100, 0xbfb8aa3b, v94
	v_mul_f32_e32 v101, 0xbfb8aa3b, v92
	v_rcp_f32_e32 v97, v97
	v_exp_f32_e32 v100, v100
	v_exp_f32_e32 v101, v101
	v_add_f32_e32 v96, 1.0, v114
	v_mul_f32_e32 v90, v90, v97
	v_add_f32_e32 v97, 1.0, v100
	v_add_f32_e32 v100, 1.0, v101
	v_rcp_f32_e32 v97, v97
	v_rcp_f32_e32 v100, v100
	v_rcp_f32_e32 v96, v96
	v_mul_f32_e32 v90, v90, v91
	v_mul_f32_e32 v91, v94, v97
	v_mul_f32_e32 v92, v92, v100
	v_mul_f32_e32 v96, v102, v96
	v_mul_f32_e32 v91, v91, v95
	v_mul_f32_e32 v93, v92, v93
	v_add_u32_e32 v99, 0x80, v188
	v_mul_f32_e32 v96, v96, v103
	v_cvt_pk_bf16_f32 v92, v96, v90
	v_cvt_pk_bf16_f32 v93, v91, v93
	v_mov_b64_e32 v[90:91], s[12:13]
	v_mad_i64_i32 v[94:95], s[38:39], v99, s72, v[90:91]
	v_lshl_add_u64 v[96:97], v[94:95], 0, v[138:139]
	v_mov_b32_e32 v248, v92
	v_mov_b32_e32 v249, v93
	v_mov_b32_dpp v99, v86 row_ror:1 row_mask:0xf bank_mask:0xf
	v_mov_b32_e32 v92, v86
	v_mov_b32_e32 v93, v82
	v_mov_b32_dpp v142, v82 row_ror:1 row_mask:0xf bank_mask:0xf
	v_mov_b32_dpp v114, v86 row_ror:2 row_mask:0xf bank_mask:0xf
	v_cndmask_b32_e64 v101, v142, v143, s[8:9]
	v_mov_b32_dpp v171, v82 row_ror:2 row_mask:0xf bank_mask:0xf
	v_cndmask_b32_e64 v100, v99, v108, s[8:9]
	v_pk_fma_f32 v[92:93], v[92:93], v[144:145], v[146:147]
	v_cndmask_b32_e64 v103, v171, v170, s[6:7]
	v_cndmask_b32_e64 v102, v114, v109, s[6:7]
	v_pk_fma_f32 v[92:93], v[160:161], v[100:101], v[92:93]
	v_pk_fma_f32 v[92:93], v[162:163], v[102:103], v[92:93]
	v_mov_b32_dpp v102, v83 row_ror:1 row_mask:0xf bank_mask:0xf
	v_mov_b32_dpp v116, v87 row_ror:1 row_mask:0xf bank_mask:0xf
	v_mov_b32_dpp v128, v87 row_ror:2 row_mask:0xf bank_mask:0xf
	v_mov_b32_e32 v86, v87
	v_mov_b32_e32 v87, v83
	v_mov_b32_dpp v103, v83 row_ror:2 row_mask:0xf bank_mask:0xf
	v_cndmask_b32_e64 v83, v102, v106, s[8:9]
	v_mov_b32_dpp v134, v88 row_ror:1 row_mask:0xf bank_mask:0xf
	v_mov_b32_e32 v94, v88
	v_mov_b32_e32 v95, v84
	v_cndmask_b32_e64 v82, v116, v111, s[8:9]
	v_cndmask_b32_e64 v101, v103, v107, s[6:7]
	v_pk_fma_f32 v[86:87], v[86:87], v[158:159], v[130:131]
	v_mov_b32_dpp v106, v84 row_ror:1 row_mask:0xf bank_mask:0xf
	v_mov_b32_dpp v135, v88 row_ror:2 row_mask:0xf bank_mask:0xf
	v_cndmask_b32_e64 v100, v128, v113, s[6:7]
	v_pk_fma_f32 v[82:83], v[156:157], v[82:83], v[86:87]
	v_mov_b32_dpp v107, v84 row_ror:2 row_mask:0xf bank_mask:0xf
	v_cndmask_b32_e64 v87, v106, v110, s[8:9]
	v_cndmask_b32_e64 v86, v134, v115, s[8:9]
	v_pk_fma_f32 v[94:95], v[94:95], v[140:141], v[164:165]
	v_pk_fma_f32 v[82:83], v[154:155], v[100:101], v[82:83]
	v_cndmask_b32_e64 v101, v107, v112, s[6:7]
	v_cndmask_b32_e64 v100, v135, v117, s[6:7]
	v_pk_fma_f32 v[86:87], v[166:167], v[86:87], v[94:95]
	v_pk_fma_f32 v[86:87], v[168:169], v[100:101], v[86:87]
	v_mov_b32_dpp v100, v85 row_ror:1 row_mask:0xf bank_mask:0xf
	v_mul_f32_e32 v94, 0xbfb8aa3b, v92
	v_mov_b32_dpp v136, v89 row_ror:1 row_mask:0xf bank_mask:0xf
	v_mov_b32_dpp v137, v89 row_ror:2 row_mask:0xf bank_mask:0xf
	v_mov_b32_e32 v88, v89
	v_mov_b32_e32 v89, v85
	v_mov_b32_dpp v101, v85 row_ror:2 row_mask:0xf bank_mask:0xf
	v_cndmask_b32_e64 v85, v100, v104, s[8:9]
	v_exp_f32_e32 v104, v94
	v_cndmask_b32_e64 v84, v136, v127, s[8:9]
	v_pk_fma_f32 v[88:89], v[88:89], v[152:153], v[132:133]
	v_cndmask_b32_e64 v95, v101, v105, s[6:7]
	v_pk_fma_f32 v[84:85], v[150:151], v[84:85], v[88:89]
	v_add_f32_e32 v88, 1.0, v104
	v_rcp_f32_e32 v88, v88
	v_mul_f32_e32 v89, 0xbfb8aa3b, v82
	v_exp_f32_e32 v89, v89
	v_cndmask_b32_e64 v94, v137, v129, s[6:7]
	v_pk_fma_f32 v[84:85], v[148:149], v[94:95], v[84:85]
	v_mul_f32_e32 v88, v92, v88
	v_mul_f32_e32 v88, v88, v93
	v_add_f32_e32 v89, 1.0, v89
	v_mul_f32_e32 v92, 0xbfb8aa3b, v86
	v_mul_f32_e32 v93, 0xbfb8aa3b, v84
	v_rcp_f32_e32 v89, v89
	v_exp_f32_e32 v92, v92
	v_exp_f32_e32 v93, v93
	v_mul_f32_e32 v82, v82, v89
	v_add_f32_e32 v89, 1.0, v92
	v_add_f32_e32 v92, 1.0, v93
	v_rcp_f32_e32 v89, v89
	v_rcp_f32_e32 v92, v92
	v_mul_f32_e32 v82, v82, v83
	v_cvt_pk_bf16_f32 v82, v88, v82
	v_mul_f32_e32 v83, v86, v89
	v_mul_f32_e32 v84, v84, v92
	v_mul_f32_e32 v83, v83, v87
	v_mul_f32_e32 v84, v84, v85
	v_add_u32_e32 v85, 0x90, v188
	v_cvt_pk_bf16_f32 v83, v83, v84
	v_mad_i64_i32 v[84:85], s[38:39], v85, s72, v[90:91]
	v_lshl_add_u64 v[126:127], v[84:85], 0, v[138:139]
	v_mov_b32_e32 v250, v82
	v_mov_b32_e32 v251, v83
	v_mov_b32_dpp v92, v78 row_ror:1 row_mask:0xf bank_mask:0xf
	v_mov_b32_e32 v82, v78
	v_mov_b32_e32 v83, v74
	v_mov_b32_dpp v110, v74 row_ror:1 row_mask:0xf bank_mask:0xf
	v_mov_b32_dpp v93, v78 row_ror:2 row_mask:0xf bank_mask:0xf
	v_cndmask_b32_e64 v87, v110, v142, s[8:9]
	v_mov_b32_dpp v111, v74 row_ror:2 row_mask:0xf bank_mask:0xf
	v_cndmask_b32_e64 v86, v92, v99, s[8:9]
	v_pk_fma_f32 v[82:83], v[82:83], v[144:145], v[146:147]
	v_cndmask_b32_e64 v89, v111, v171, s[6:7]
	v_cndmask_b32_e64 v88, v93, v114, s[6:7]
	v_pk_fma_f32 v[82:83], v[160:161], v[86:87], v[82:83]
	v_pk_fma_f32 v[82:83], v[162:163], v[88:89], v[82:83]
	v_mov_b32_dpp v94, v79 row_ror:1 row_mask:0xf bank_mask:0xf
	v_mov_b32_dpp v95, v79 row_ror:2 row_mask:0xf bank_mask:0xf
	v_mov_b32_e32 v78, v79
	v_mov_b32_e32 v79, v75
	v_mov_b32_dpp v88, v75 row_ror:1 row_mask:0xf bank_mask:0xf
	v_mov_b32_dpp v104, v80 row_ror:1 row_mask:0xf bank_mask:0xf
	v_mov_b32_e32 v84, v80
	v_mov_b32_e32 v85, v76
	v_mov_b32_dpp v89, v75 row_ror:2 row_mask:0xf bank_mask:0xf
	v_cndmask_b32_e64 v75, v88, v102, s[8:9]
	v_cndmask_b32_e64 v74, v94, v116, s[8:9]
	v_pk_fma_f32 v[78:79], v[78:79], v[158:159], v[130:131]
	v_mov_b32_dpp v99, v76 row_ror:1 row_mask:0xf bank_mask:0xf
	v_mov_b32_dpp v105, v80 row_ror:2 row_mask:0xf bank_mask:0xf
	v_cndmask_b32_e64 v87, v89, v103, s[6:7]
	v_cndmask_b32_e64 v86, v95, v128, s[6:7]
	v_pk_fma_f32 v[74:75], v[156:157], v[74:75], v[78:79]
	v_mov_b32_dpp v102, v76 row_ror:2 row_mask:0xf bank_mask:0xf
	v_cndmask_b32_e64 v79, v99, v106, s[8:9]
	v_cndmask_b32_e64 v78, v104, v134, s[8:9]
	v_pk_fma_f32 v[84:85], v[84:85], v[140:141], v[164:165]
	v_pk_fma_f32 v[74:75], v[154:155], v[86:87], v[74:75]
	v_cndmask_b32_e64 v87, v102, v107, s[6:7]
	v_cndmask_b32_e64 v86, v105, v135, s[6:7]
	v_pk_fma_f32 v[78:79], v[166:167], v[78:79], v[84:85]
	v_pk_fma_f32 v[78:79], v[168:169], v[86:87], v[78:79]
	v_mov_b32_dpp v86, v77 row_ror:1 row_mask:0xf bank_mask:0xf
	v_mul_f32_e32 v84, 0xbfb8aa3b, v82
	v_mov_b32_dpp v108, v81 row_ror:1 row_mask:0xf bank_mask:0xf
	v_mov_b32_dpp v109, v81 row_ror:2 row_mask:0xf bank_mask:0xf
	v_mov_b32_e32 v80, v81
	v_mov_b32_e32 v81, v77
	v_mov_b32_dpp v87, v77 row_ror:2 row_mask:0xf bank_mask:0xf
	v_cndmask_b32_e64 v77, v86, v100, s[8:9]
	v_exp_f32_e32 v100, v84
	v_cndmask_b32_e64 v76, v108, v136, s[8:9]
	v_pk_fma_f32 v[80:81], v[80:81], v[152:153], v[132:133]
	v_cndmask_b32_e64 v85, v87, v101, s[6:7]
	v_pk_fma_f32 v[76:77], v[150:151], v[76:77], v[80:81]
	v_add_f32_e32 v80, 1.0, v100
	v_rcp_f32_e32 v80, v80
	v_mul_f32_e32 v81, 0xbfb8aa3b, v74
	v_exp_f32_e32 v81, v81
	v_cndmask_b32_e64 v84, v109, v137, s[6:7]
	v_pk_fma_f32 v[76:77], v[148:149], v[84:85], v[76:77]
	v_mul_f32_e32 v80, v82, v80
	v_mul_f32_e32 v80, v80, v83
	v_add_f32_e32 v81, 1.0, v81
	v_mul_f32_e32 v82, 0xbfb8aa3b, v78
	v_mul_f32_e32 v83, 0xbfb8aa3b, v76
	v_rcp_f32_e32 v81, v81
	v_exp_f32_e32 v82, v82
	v_exp_f32_e32 v83, v83
	v_mul_f32_e32 v74, v74, v81
	v_add_f32_e32 v81, 1.0, v82
	v_add_f32_e32 v82, 1.0, v83
	v_rcp_f32_e32 v81, v81
	v_rcp_f32_e32 v82, v82
	v_mul_f32_e32 v74, v74, v75
	v_cvt_pk_bf16_f32 v74, v80, v74
	v_mul_f32_e32 v75, v78, v81
	v_mul_f32_e32 v76, v76, v82
	v_mul_f32_e32 v75, v75, v79
	v_mul_f32_e32 v76, v76, v77
	v_add_u32_e32 v77, 0xa0, v188
	v_cvt_pk_bf16_f32 v75, v75, v76
	v_mad_i64_i32 v[76:77], s[38:39], v77, s72, v[90:91]
	v_lshl_add_u64 v[128:129], v[76:77], 0, v[138:139]
	v_mov_b32_e32 v252, v74
	v_mov_b32_e32 v253, v75
	v_mov_b32_dpp v78, v70 row_ror:1 row_mask:0xf bank_mask:0xf
	v_mov_b32_e32 v74, v70
	v_mov_b32_e32 v75, v66
	v_mov_b32_dpp v79, v66 row_ror:1 row_mask:0xf bank_mask:0xf
	v_mov_b32_dpp v81, v66 row_ror:2 row_mask:0xf bank_mask:0xf
	v_cndmask_b32_e64 v79, v79, v110, s[8:9]
	v_cndmask_b32_e64 v78, v78, v92, s[8:9]
	v_pk_fma_f32 v[74:75], v[74:75], v[144:145], v[146:147]
	v_mov_b32_dpp v80, v70 row_ror:2 row_mask:0xf bank_mask:0xf
	v_mov_b32_dpp v82, v71 row_ror:1 row_mask:0xf bank_mask:0xf
	v_mov_b32_dpp v83, v71 row_ror:2 row_mask:0xf bank_mask:0xf
	v_mov_b32_e32 v70, v71
	v_mov_b32_e32 v71, v67
	v_pk_fma_f32 v[74:75], v[160:161], v[78:79], v[74:75]
	v_mov_b32_dpp v66, v67 row_ror:1 row_mask:0xf bank_mask:0xf
	v_pk_fma_f32 v[70:71], v[70:71], v[158:159], v[130:131]
	v_mov_b32_dpp v84, v72 row_ror:1 row_mask:0xf bank_mask:0xf
	v_mov_b32_dpp v78, v67 row_ror:2 row_mask:0xf bank_mask:0xf
	v_cndmask_b32_e64 v67, v66, v88, s[8:9]
	v_cndmask_b32_e64 v66, v82, v94, s[8:9]
	v_pk_fma_f32 v[66:67], v[156:157], v[66:67], v[70:71]
	v_mov_b32_e32 v76, v72
	v_mov_b32_e32 v77, v68
	v_mov_b32_dpp v70, v68 row_ror:1 row_mask:0xf bank_mask:0xf
	v_cndmask_b32_e64 v79, v78, v89, s[6:7]
	v_cndmask_b32_e64 v78, v83, v95, s[6:7]
	v_cndmask_b32_e64 v71, v70, v99, s[8:9]
	v_cndmask_b32_e64 v70, v84, v104, s[8:9]
	v_pk_fma_f32 v[76:77], v[76:77], v[140:141], v[164:165]
	v_cndmask_b32_e64 v81, v81, v111, s[6:7]
	v_cndmask_b32_e64 v80, v80, v93, s[6:7]
	v_pk_fma_f32 v[66:67], v[154:155], v[78:79], v[66:67]
	v_pk_fma_f32 v[70:71], v[166:167], v[70:71], v[76:77]
	v_mov_b32_dpp v85, v72 row_ror:2 row_mask:0xf bank_mask:0xf
	v_pk_fma_f32 v[74:75], v[162:163], v[80:81], v[74:75]
	v_mov_b32_dpp v78, v68 row_ror:2 row_mask:0xf bank_mask:0xf
	v_mov_b32_dpp v76, v69 row_ror:2 row_mask:0xf bank_mask:0xf
	v_cndmask_b32_e64 v79, v78, v102, s[6:7]
	v_cndmask_b32_e64 v78, v85, v105, s[6:7]
	v_cndmask_b32_e64 v77, v76, v87, s[6:7]
	v_mul_f32_e32 v76, 0xbfb8aa3b, v74
	v_pk_fma_f32 v[70:71], v[168:169], v[78:79], v[70:71]
	v_exp_f32_e32 v78, v76
	v_mov_b32_dpp v100, v73 row_ror:1 row_mask:0xf bank_mask:0xf
	v_mov_b32_dpp v101, v73 row_ror:2 row_mask:0xf bank_mask:0xf
	v_mov_b32_e32 v72, v73
	v_mov_b32_e32 v73, v69
	v_mov_b32_dpp v68, v69 row_ror:1 row_mask:0xf bank_mask:0xf
	v_cndmask_b32_e64 v69, v68, v86, s[8:9]
	v_cndmask_b32_e64 v68, v100, v108, s[8:9]
	v_pk_fma_f32 v[72:73], v[72:73], v[152:153], v[132:133]
	v_cndmask_b32_e64 v76, v101, v109, s[6:7]
	v_pk_fma_f32 v[68:69], v[150:151], v[68:69], v[72:73]
	v_add_f32_e32 v72, 1.0, v78
	v_rcp_f32_e32 v72, v72
	v_mul_f32_e32 v73, 0xbfb8aa3b, v66
	v_exp_f32_e32 v73, v73
	v_pk_fma_f32 v[68:69], v[148:149], v[76:77], v[68:69]
	v_mul_f32_e32 v72, v74, v72
	v_mul_f32_e32 v72, v72, v75
	v_add_f32_e32 v73, 1.0, v73
	v_mul_f32_e32 v74, 0xbfb8aa3b, v70
	v_mul_f32_e32 v75, 0xbfb8aa3b, v68
	v_rcp_f32_e32 v73, v73
	v_exp_f32_e32 v74, v74
	v_exp_f32_e32 v75, v75
	v_mov_b32_e32 v98, 0
	v_mul_f32_e32 v66, v66, v73
	v_add_f32_e32 v73, 1.0, v74
	v_add_f32_e32 v74, 1.0, v75
	v_rcp_f32_e32 v73, v73
	v_rcp_f32_e32 v74, v74
	v_mul_f32_e32 v66, v66, v67
	v_cvt_pk_bf16_f32 v66, v72, v66
	v_mul_f32_e32 v67, v70, v73
	v_mul_f32_e32 v68, v68, v74
	v_mul_f32_e32 v67, v67, v71
	v_mul_f32_e32 v68, v68, v69
	v_add_u32_e32 v69, 0xb0, v188
	v_cvt_pk_bf16_f32 v67, v67, v68
	v_mad_i64_i32 v[68:69], s[38:39], v69, s72, v[90:91]
	v_lshl_add_u64 v[130:131], v[68:69], 0, v[138:139]
	v_mov_b32_e32 v230, v66
	v_mov_b32_e32 v231, v67
	v_add_co_u32_e32 v66, vcc, 0x15000, v206
	v_mov_b32_e32 v70, s94
	global_load_dwordx4 v[72:75], v[210:211], off offset:16
	global_load_dwordx4 v[80:83], v[206:207], off offset:16
	v_addc_co_u32_e32 v67, vcc, 0, v207, vcc
	v_add_co_u32_e32 v68, vcc, 0x2b000, v206
	s_nop 1
	v_addc_co_u32_e32 v69, vcc, 0, v207, vcc
	global_load_dwordx4 v[88:91], v[66:67], off offset:2064
	global_load_dwordx4 v[84:87], v[68:69], off offset:16
	v_add_co_u32_e32 v66, vcc, 0xa000, v210
	s_nop 1
	v_addc_co_u32_e32 v67, vcc, 0, v211, vcc
	v_add_co_u32_e32 v76, vcc, 0xa000, v206
	global_load_dwordx4 v[66:69], v[66:67], off offset:3088
	s_nop 0
	global_load_dwordx4 v[114:117], v[208:209], off offset:16
	global_load_dwordx4 v[92:95], v[208:209], off offset:528
	v_addc_co_u32_e32 v77, vcc, 0, v207, vcc
	v_add_co_u32_e32 v78, vcc, 0x20000, v206
	s_nop 1
	v_addc_co_u32_e32 v79, vcc, 0, v207, vcc
	global_load_dwordx4 v[106:109], v[76:77], off offset:3088
	global_load_dwordx4 v[102:105], v[78:79], off offset:1040
	v_add_co_u32_e32 v76, vcc, 0x35000, v206
	v_mov_b32_e32 v78, 0
	s_nop 0
	v_addc_co_u32_e32 v77, vcc, 0, v207, vcc
	global_load_dwordx4 v[110:113], v[76:77], off offset:3088
	v_mov_b32_e32 v76, 0
	v_mov_b32_e32 v77, 0
	v_mov_b32_e32 v79, 0
	s_and_saveexec_b64 s[38:39], s[26:27]
	ds_read_b128 v[76:79], v217
	s_or_b64 exec, exec, s[38:39]
	v_mov_b32_e32 v99, 0
	v_mov_b32_e32 v100, 0
	v_mov_b32_e32 v101, 0
	s_and_saveexec_b64 s[38:39], s[26:27]
	ds_read_b128 v[98:101], v217 offset:512
	s_or_b64 exec, exec, s[38:39]
	s_waitcnt vmcnt(4)
	v_pk_mul_f32 v[114:115], v[114:115], v[70:71] op_sel_hi:[1,0]
	v_pk_mul_f32 v[116:117], v[116:117], v[70:71] op_sel_hi:[1,0]
	v_pk_mul_f32 v[134:135], v[80:81], v[114:115]
	v_pk_mul_f32 v[138:139], v[114:115], v[88:89]
	v_pk_mul_f32 v[114:115], v[114:115], v[84:85]
	s_waitcnt vmcnt(3)
	v_pk_mul_f32 v[84:85], v[70:71], v[94:95] op_sel_hi:[0,1]
	v_pk_mul_f32 v[70:71], v[70:71], v[92:93] op_sel_hi:[0,1]
	v_pk_mul_f32 v[132:133], v[82:83], v[116:117]
	v_pk_mul_f32 v[136:137], v[116:117], v[90:91]
	v_pk_mul_f32 v[116:117], v[116:117], v[86:87]
	s_waitcnt vmcnt(2)
	v_pk_mul_f32 v[86:87], v[106:107], v[70:71]
	s_waitcnt vmcnt(1)
	v_pk_mul_f32 v[88:89], v[70:71], v[102:103]
	s_waitcnt vmcnt(0)
	v_pk_mul_f32 v[90:91], v[70:71], v[110:111]
	s_waitcnt lgkmcnt(0)
	v_mov_b32_dpp v92, v76 row_ror:1 row_mask:0xf bank_mask:0xf
	v_mov_b32_dpp v93, v76 row_ror:2 row_mask:0xf bank_mask:0xf
	v_mov_b32_dpp v106, v77 row_ror:1 row_mask:0xf bank_mask:0xf
	v_mov_b32_dpp v107, v77 row_ror:2 row_mask:0xf bank_mask:0xf
	v_pk_mul_f32 v[80:81], v[108:109], v[84:85]
	v_mov_b32_dpp v71, v62 row_ror:1 row_mask:0xf bank_mask:0xf
	v_mov_b32_dpp v110, v62 row_ror:2 row_mask:0xf bank_mask:0xf
	v_mov_b32_dpp v145, v58 row_ror:1 row_mask:0xf bank_mask:0xf
	v_mov_b32_dpp v76, v98 row_ror:1 row_mask:0xf bank_mask:0xf
	v_mov_b32_dpp v146, v58 row_ror:2 row_mask:0xf bank_mask:0xf
	v_mov_b32_dpp v77, v98 row_ror:2 row_mask:0xf bank_mask:0xf
	v_mov_b32_dpp v108, v78 row_ror:1 row_mask:0xf bank_mask:0xf
	v_mov_b32_dpp v109, v78 row_ror:2 row_mask:0xf bank_mask:0xf
	v_mov_b32_dpp v142, v79 row_ror:1 row_mask:0xf bank_mask:0xf
	v_mov_b32_dpp v144, v79 row_ror:2 row_mask:0xf bank_mask:0xf
	v_cndmask_b32_e64 v95, v145, v76, s[8:9]
	v_cndmask_b32_e64 v94, v71, v92, s[8:9]
	v_cndmask_b32_e64 v103, v146, v77, s[6:7]
	v_cndmask_b32_e64 v102, v110, v93, s[6:7]
	v_mov_b32_e32 v92, v62
	v_mov_b32_e32 v93, v58
	v_mov_b32_e32 v76, v114
	v_mov_b32_e32 v77, v90
	v_mov_b32_e32 v78, v72
	v_mov_b32_e32 v79, v66
	v_pk_mul_f32 v[82:83], v[84:85], v[104:105]
	v_pk_fma_f32 v[104:105], v[92:93], v[76:77], v[78:79]
	v_mov_b32_e32 v92, v138
	v_mov_b32_e32 v93, v88
	v_mov_b32_dpp v114, v59 row_ror:1 row_mask:0xf bank_mask:0xf
	v_mov_b32_dpp v58, v99 row_ror:1 row_mask:0xf bank_mask:0xf
	v_pk_mul_f32 v[84:85], v[84:85], v[112:113]
	v_mov_b32_dpp v111, v63 row_ror:1 row_mask:0xf bank_mask:0xf
	v_pk_fma_f32 v[104:105], v[92:93], v[94:95], v[104:105]
	v_mov_b32_e32 v94, v134
	v_mov_b32_dpp v62, v99 row_ror:2 row_mask:0xf bank_mask:0xf
	v_cndmask_b32_e64 v99, v114, v58, s[8:9]
	v_mov_b32_e32 v58, v63
	v_mov_b32_e32 v90, v115
	v_mov_b32_e32 v66, v73
	v_mov_b32_dpp v112, v63 row_ror:2 row_mask:0xf bank_mask:0xf
	v_mov_b32_e32 v95, v86
	v_mov_b32_dpp v134, v59 row_ror:2 row_mask:0xf bank_mask:0xf
	v_cndmask_b32_e64 v98, v111, v106, s[8:9]
	v_pk_fma_f32 v[58:59], v[58:59], v[90:91], v[66:67]
	v_mov_b32_e32 v88, v139
	v_pk_fma_f32 v[104:105], v[94:95], v[102:103], v[104:105]
	v_cndmask_b32_e64 v103, v134, v62, s[6:7]
	v_cndmask_b32_e64 v102, v112, v107, s[6:7]
	v_pk_fma_f32 v[58:59], v[88:89], v[98:99], v[58:59]
	v_mov_b32_e32 v86, v135
	v_pk_fma_f32 v[72:73], v[86:87], v[102:103], v[58:59]
	v_mov_b32_dpp v115, v60 row_ror:1 row_mask:0xf bank_mask:0xf
	v_mov_b32_dpp v135, v60 row_ror:2 row_mask:0xf bank_mask:0xf
	v_mov_b32_e32 v99, v60
	v_mov_b32_e32 v62, v74
	v_mov_b32_dpp v113, v64 row_ror:1 row_mask:0xf bank_mask:0xf
	v_mov_b32_dpp v140, v64 row_ror:2 row_mask:0xf bank_mask:0xf
	v_mov_b32_dpp v58, v100 row_ror:1 row_mask:0xf bank_mask:0xf
	v_mov_b32_dpp v59, v100 row_ror:2 row_mask:0xf bank_mask:0xf
	v_mov_b32_e32 v98, v64
	v_mov_b32_dpp v74, v61 row_ror:1 row_mask:0xf bank_mask:0xf
	v_mov_b32_dpp v60, v101 row_ror:1 row_mask:0xf bank_mask:0xf
	v_mov_b32_dpp v141, v65 row_ror:1 row_mask:0xf bank_mask:0xf
	v_mov_b32_dpp v143, v65 row_ror:2 row_mask:0xf bank_mask:0xf
	v_cndmask_b32_e64 v103, v115, v58, s[8:9]
	v_cndmask_b32_e64 v107, v135, v59, s[6:7]
	v_mov_b32_e32 v58, v116
	v_mov_b32_e32 v59, v84
	v_mov_b32_e32 v63, v68
	v_mov_b32_dpp v64, v101 row_ror:2 row_mask:0xf bank_mask:0xf
	v_cndmask_b32_e64 v101, v74, v60, s[8:9]
	v_mov_b32_e32 v60, v65
	v_mul_f32_e32 v65, 0xbfb8aa3b, v72
	v_cndmask_b32_e64 v102, v113, v108, s[8:9]
	v_cndmask_b32_e64 v106, v140, v109, s[6:7]
	v_pk_fma_f32 v[108:109], v[98:99], v[58:59], v[62:63]
	v_mov_b32_e32 v98, v136
	v_mov_b32_e32 v99, v82
	v_mov_b32_e32 v84, v117
	v_mov_b32_e32 v68, v75
	v_exp_f32_e32 v65, v65
	v_pk_fma_f32 v[108:109], v[98:99], v[102:103], v[108:109]
	v_mov_b32_e32 v102, v132
	v_mov_b32_e32 v103, v80
	v_mov_b32_dpp v116, v61 row_ror:2 row_mask:0xf bank_mask:0xf
	v_cndmask_b32_e64 v100, v141, v142, s[8:9]
	v_pk_fma_f32 v[60:61], v[60:61], v[84:85], v[68:69]
	v_mov_b32_e32 v82, v137
	v_pk_fma_f32 v[106:107], v[102:103], v[106:107], v[108:109]
	v_cndmask_b32_e64 v109, v116, v64, s[6:7]
	v_cndmask_b32_e64 v108, v143, v144, s[6:7]
	v_pk_fma_f32 v[60:61], v[82:83], v[100:101], v[60:61]
	v_mov_b32_e32 v80, v133
	v_pk_fma_f32 v[60:61], v[80:81], v[108:109], v[60:61]
	v_add_f32_e32 v65, 1.0, v65
	v_mul_f32_e32 v75, 0xbfb8aa3b, v106
	v_mul_f32_e32 v100, 0xbfb8aa3b, v60
	v_mul_f32_e32 v64, 0xbfb8aa3b, v104
	v_rcp_f32_e32 v65, v65
	v_exp_f32_e32 v75, v75
	v_exp_f32_e32 v100, v100
	v_exp_f32_e32 v64, v64
	v_mul_f32_e32 v65, v72, v65
	v_add_f32_e32 v72, 1.0, v75
	v_add_f32_e32 v75, 1.0, v100
	v_add_f32_e32 v64, 1.0, v64
	v_rcp_f32_e32 v72, v72
	v_rcp_f32_e32 v75, v75
	v_rcp_f32_e32 v64, v64
	v_mul_f32_e32 v72, v106, v72
	v_mul_f32_e32 v60, v60, v75
	v_mul_f32_e32 v64, v104, v64
	v_mul_f32_e32 v72, v72, v107
	v_mul_f32_e32 v61, v60, v61
	v_mul_f32_e32 v64, v64, v105
	v_mul_f32_e32 v65, v65, v73
	v_cvt_pk_bf16_f32 v60, v64, v65
	v_cvt_pk_bf16_f32 v61, v72, v61
	v_mov_b32_dpp v75, v54 row_ror:1 row_mask:0xf bank_mask:0xf
	v_mov_b32_dpp v109, v50 row_ror:1 row_mask:0xf bank_mask:0xf
	v_mov_b32_e32 v72, v54
	v_mov_b32_e32 v73, v50
	v_mov_b32_e32 v148, v240
	v_mov_b32_e32 v149, v241
	v_mov_b32_e32 v150, v60
	v_mov_b32_e32 v151, v61
	global_store_dwordx4 v[122:123], v[148:151], off
	v_mov_b32_dpp v100, v54 row_ror:2 row_mask:0xf bank_mask:0xf
	v_mov_b32_dpp v117, v50 row_ror:2 row_mask:0xf bank_mask:0xf
	v_cndmask_b32_e64 v61, v109, v145, s[8:9]
	v_cndmask_b32_e64 v60, v75, v71, s[8:9]
	v_pk_fma_f32 v[72:73], v[72:73], v[76:77], v[78:79]
	v_mov_b32_dpp v101, v55 row_ror:1 row_mask:0xf bank_mask:0xf
	v_cndmask_b32_e64 v65, v117, v146, s[6:7]
	v_cndmask_b32_e64 v64, v100, v110, s[6:7]
	v_pk_fma_f32 v[60:61], v[92:93], v[60:61], v[72:73]
	v_mov_b32_dpp v71, v51 row_ror:1 row_mask:0xf bank_mask:0xf
	v_mov_b32_e32 v50, v55
	v_mov_b32_dpp v104, v55 row_ror:2 row_mask:0xf bank_mask:0xf
	v_pk_fma_f32 v[60:61], v[94:95], v[64:65], v[60:61]
	v_mov_b32_dpp v110, v51 row_ror:2 row_mask:0xf bank_mask:0xf
	v_cndmask_b32_e64 v65, v71, v114, s[8:9]
	v_cndmask_b32_e64 v64, v101, v111, s[8:9]
	v_pk_fma_f32 v[50:51], v[50:51], v[90:91], v[66:67]
	v_cndmask_b32_e64 v73, v110, v134, s[6:7]
	v_cndmask_b32_e64 v72, v104, v112, s[6:7]
	v_pk_fma_f32 v[50:51], v[88:89], v[64:65], v[50:51]
	v_mov_b32_dpp v105, v56 row_ror:1 row_mask:0xf bank_mask:0xf
	v_pk_fma_f32 v[50:51], v[86:87], v[72:73], v[50:51]
	v_mov_b32_dpp v111, v52 row_ror:1 row_mask:0xf bank_mask:0xf
	v_mov_b32_e32 v72, v56
	v_mov_b32_e32 v73, v52
	v_mov_b32_dpp v106, v56 row_ror:2 row_mask:0xf bank_mask:0xf
	v_mov_b32_dpp v112, v52 row_ror:2 row_mask:0xf bank_mask:0xf
	v_cndmask_b32_e64 v55, v111, v115, s[8:9]
	v_cndmask_b32_e64 v54, v105, v113, s[8:9]
	v_pk_fma_f32 v[72:73], v[72:73], v[58:59], v[62:63]
	v_cndmask_b32_e64 v65, v112, v135, s[6:7]
	v_cndmask_b32_e64 v64, v106, v140, s[6:7]
	v_pk_fma_f32 v[54:55], v[98:99], v[54:55], v[72:73]
	v_mov_b32_dpp v56, v53 row_ror:1 row_mask:0xf bank_mask:0xf
	v_mul_f32_e32 v52, 0xbfb8aa3b, v60
	v_pk_fma_f32 v[54:55], v[102:103], v[64:65], v[54:55]
	v_cndmask_b32_e64 v65, v56, v74, s[8:9]
	v_exp_f32_e32 v74, v52
	v_mov_b32_dpp v107, v57 row_ror:1 row_mask:0xf bank_mask:0xf
	v_mov_b32_e32 v52, v57
	v_mov_b32_dpp v108, v57 row_ror:2 row_mask:0xf bank_mask:0xf
	v_mov_b32_dpp v113, v53 row_ror:2 row_mask:0xf bank_mask:0xf
	v_cndmask_b32_e64 v64, v107, v141, s[8:9]
	v_pk_fma_f32 v[52:53], v[52:53], v[84:85], v[68:69]
	v_add_f32_e32 v57, 1.0, v74
	v_pk_fma_f32 v[52:53], v[82:83], v[64:65], v[52:53]
	v_rcp_f32_e32 v57, v57
	v_mul_f32_e32 v64, 0xbfb8aa3b, v50
	v_exp_f32_e32 v64, v64
	v_cndmask_b32_e64 v73, v113, v116, s[6:7]
	v_cndmask_b32_e64 v72, v108, v143, s[6:7]
	v_mul_f32_e32 v57, v60, v57
	v_pk_fma_f32 v[52:53], v[80:81], v[72:73], v[52:53]
	v_mul_f32_e32 v57, v57, v61
	v_add_f32_e32 v60, 1.0, v64
	v_mul_f32_e32 v61, 0xbfb8aa3b, v54
	v_rcp_f32_e32 v60, v60
	v_exp_f32_e32 v61, v61
	v_mul_f32_e32 v64, 0xbfb8aa3b, v52
	v_exp_f32_e32 v64, v64
	v_mul_f32_e32 v50, v50, v60
	v_add_f32_e32 v60, 1.0, v61
	v_rcp_f32_e32 v60, v60
	v_add_f32_e32 v61, 1.0, v64
	v_rcp_f32_e32 v61, v61
	v_mul_f32_e32 v50, v50, v51
	v_mul_f32_e32 v51, v54, v60
	v_mul_f32_e32 v51, v51, v55
	v_mul_f32_e32 v52, v52, v61
	v_cvt_pk_bf16_f32 v50, v57, v50
	v_mul_f32_e32 v52, v52, v53
	v_cvt_pk_bf16_f32 v51, v51, v52
	v_mov_b32_dpp v57, v46 row_ror:1 row_mask:0xf bank_mask:0xf
	v_mov_b32_dpp v114, v42 row_ror:1 row_mask:0xf bank_mask:0xf
	v_mov_b32_e32 v54, v46
	v_mov_b32_e32 v55, v42
	v_mov_b32_e32 v152, v242
	v_mov_b32_e32 v153, v243
	v_mov_b32_e32 v154, v50
	v_mov_b32_e32 v155, v51
	global_store_dwordx4 v[118:119], v[152:155], off
	v_mov_b32_dpp v60, v46 row_ror:2 row_mask:0xf bank_mask:0xf
	v_mov_b32_dpp v115, v42 row_ror:2 row_mask:0xf bank_mask:0xf
	v_cndmask_b32_e64 v51, v114, v109, s[8:9]
	v_cndmask_b32_e64 v50, v57, v75, s[8:9]
	v_pk_fma_f32 v[54:55], v[54:55], v[76:77], v[78:79]
	v_mov_b32_dpp v61, v47 row_ror:1 row_mask:0xf bank_mask:0xf
	v_cndmask_b32_e64 v53, v115, v117, s[6:7]
	v_cndmask_b32_e64 v52, v60, v100, s[6:7]
	v_pk_fma_f32 v[50:51], v[92:93], v[50:51], v[54:55]
	v_mov_b32_dpp v75, v43 row_ror:1 row_mask:0xf bank_mask:0xf
	v_mov_b32_e32 v42, v47
	v_mov_b32_dpp v64, v47 row_ror:2 row_mask:0xf bank_mask:0xf
	v_pk_fma_f32 v[50:51], v[94:95], v[52:53], v[50:51]
	v_mov_b32_dpp v100, v43 row_ror:2 row_mask:0xf bank_mask:0xf
	v_cndmask_b32_e64 v53, v75, v71, s[8:9]
	v_cndmask_b32_e64 v52, v61, v101, s[8:9]
	v_pk_fma_f32 v[42:43], v[42:43], v[90:91], v[66:67]
	v_cndmask_b32_e64 v55, v100, v110, s[6:7]
	v_cndmask_b32_e64 v54, v64, v104, s[6:7]
	v_pk_fma_f32 v[42:43], v[88:89], v[52:53], v[42:43]
	v_mov_b32_dpp v65, v48 row_ror:1 row_mask:0xf bank_mask:0xf
	v_pk_fma_f32 v[42:43], v[86:87], v[54:55], v[42:43]
	v_mov_b32_dpp v71, v44 row_ror:1 row_mask:0xf bank_mask:0xf
	v_mov_b32_e32 v54, v48
	v_mov_b32_e32 v55, v44
	v_mov_b32_dpp v72, v48 row_ror:2 row_mask:0xf bank_mask:0xf
	v_mov_b32_dpp v101, v44 row_ror:2 row_mask:0xf bank_mask:0xf
	v_cndmask_b32_e64 v47, v71, v111, s[8:9]
	v_cndmask_b32_e64 v46, v65, v105, s[8:9]
	v_pk_fma_f32 v[54:55], v[54:55], v[58:59], v[62:63]
	v_cndmask_b32_e64 v53, v101, v112, s[6:7]
	v_cndmask_b32_e64 v52, v72, v106, s[6:7]
	v_pk_fma_f32 v[46:47], v[98:99], v[46:47], v[54:55]
	v_mov_b32_dpp v48, v45 row_ror:1 row_mask:0xf bank_mask:0xf
	v_mul_f32_e32 v44, 0xbfb8aa3b, v50
	v_pk_fma_f32 v[46:47], v[102:103], v[52:53], v[46:47]
	v_cndmask_b32_e64 v53, v48, v56, s[8:9]
	v_exp_f32_e32 v56, v44
	v_mov_b32_dpp v73, v49 row_ror:1 row_mask:0xf bank_mask:0xf
	v_mov_b32_e32 v44, v49
	v_mov_b32_dpp v74, v49 row_ror:2 row_mask:0xf bank_mask:0xf
	v_mov_b32_dpp v104, v45 row_ror:2 row_mask:0xf bank_mask:0xf
	v_cndmask_b32_e64 v52, v73, v107, s[8:9]
	v_pk_fma_f32 v[44:45], v[44:45], v[84:85], v[68:69]
	v_add_f32_e32 v49, 1.0, v56
	v_pk_fma_f32 v[44:45], v[82:83], v[52:53], v[44:45]
	v_rcp_f32_e32 v49, v49
	v_mul_f32_e32 v52, 0xbfb8aa3b, v42
	v_exp_f32_e32 v52, v52
	v_cndmask_b32_e64 v55, v104, v113, s[6:7]
	v_cndmask_b32_e64 v54, v74, v108, s[6:7]
	v_mul_f32_e32 v49, v50, v49
	v_pk_fma_f32 v[44:45], v[80:81], v[54:55], v[44:45]
	v_mul_f32_e32 v49, v49, v51
	v_add_f32_e32 v50, 1.0, v52
	v_mul_f32_e32 v51, 0xbfb8aa3b, v46
	v_rcp_f32_e32 v50, v50
	v_exp_f32_e32 v51, v51
	v_mul_f32_e32 v52, 0xbfb8aa3b, v44
	v_exp_f32_e32 v52, v52
	v_mul_f32_e32 v42, v42, v50
	v_add_f32_e32 v50, 1.0, v51
	v_rcp_f32_e32 v50, v50
	v_add_f32_e32 v51, 1.0, v52
	v_rcp_f32_e32 v51, v51
	v_mul_f32_e32 v42, v42, v43
	v_mul_f32_e32 v43, v46, v50
	v_mul_f32_e32 v43, v43, v47
	v_mul_f32_e32 v44, v44, v51
	v_mul_f32_e32 v44, v44, v45
	v_cvt_pk_bf16_f32 v42, v49, v42
	v_cvt_pk_bf16_f32 v43, v43, v44
	v_mov_b32_e32 v156, v244
	v_mov_b32_e32 v157, v245
	v_mov_b32_e32 v158, v42
	v_mov_b32_e32 v159, v43
	global_store_dwordx4 v[120:121], v[156:159], off
	v_mov_b32_dpp v42, v38 row_ror:1 row_mask:0xf bank_mask:0xf
	v_mov_b32_dpp v43, v34 row_ror:1 row_mask:0xf bank_mask:0xf
	v_mov_b32_e32 v46, v38
	v_mov_b32_e32 v47, v34
	v_mov_b32_dpp v44, v38 row_ror:2 row_mask:0xf bank_mask:0xf
	v_mov_b32_dpp v45, v34 row_ror:2 row_mask:0xf bank_mask:0xf
	v_cndmask_b32_e64 v43, v43, v114, s[8:9]
	v_cndmask_b32_e64 v42, v42, v57, s[8:9]
	v_pk_fma_f32 v[46:47], v[46:47], v[76:77], v[78:79]
	v_cndmask_b32_e64 v45, v45, v115, s[6:7]
	v_cndmask_b32_e64 v44, v44, v60, s[6:7]
	v_pk_fma_f32 v[42:43], v[92:93], v[42:43], v[46:47]
	v_mov_b32_dpp v34, v35 row_ror:1 row_mask:0xf bank_mask:0xf
	v_mov_b32_dpp v49, v39 row_ror:1 row_mask:0xf bank_mask:0xf
	v_pk_fma_f32 v[42:43], v[94:95], v[44:45], v[42:43]
	v_cndmask_b32_e64 v45, v34, v75, s[8:9]
	v_mov_b32_e32 v34, v39
	v_mov_b32_dpp v50, v39 row_ror:2 row_mask:0xf bank_mask:0xf
	v_mov_b32_dpp v38, v35 row_ror:2 row_mask:0xf bank_mask:0xf
	v_cndmask_b32_e64 v44, v49, v61, s[8:9]
	v_pk_fma_f32 v[34:35], v[34:35], v[90:91], v[66:67]
	v_cndmask_b32_e64 v47, v38, v100, s[6:7]
	v_cndmask_b32_e64 v46, v50, v64, s[6:7]
	v_pk_fma_f32 v[34:35], v[88:89], v[44:45], v[34:35]
	v_mov_b32_dpp v51, v40 row_ror:1 row_mask:0xf bank_mask:0xf
	v_pk_fma_f32 v[34:35], v[86:87], v[46:47], v[34:35]
	v_mov_b32_dpp v38, v36 row_ror:1 row_mask:0xf bank_mask:0xf
	v_mov_b32_e32 v46, v40
	v_mov_b32_e32 v47, v36
	v_mov_b32_dpp v52, v40 row_ror:2 row_mask:0xf bank_mask:0xf
	v_mov_b32_dpp v44, v36 row_ror:2 row_mask:0xf bank_mask:0xf
	v_cndmask_b32_e64 v39, v38, v71, s[8:9]
	v_cndmask_b32_e64 v38, v51, v65, s[8:9]
	v_pk_fma_f32 v[46:47], v[46:47], v[58:59], v[62:63]
	v_cndmask_b32_e64 v45, v44, v101, s[6:7]
	v_cndmask_b32_e64 v44, v52, v72, s[6:7]
	v_pk_fma_f32 v[38:39], v[98:99], v[38:39], v[46:47]
	v_mov_b32_dpp v36, v37 row_ror:1 row_mask:0xf bank_mask:0xf
	v_pk_fma_f32 v[38:39], v[102:103], v[44:45], v[38:39]
	v_cndmask_b32_e64 v45, v36, v48, s[8:9]
	v_mov_b32_dpp v40, v37 row_ror:2 row_mask:0xf bank_mask:0xf
	v_mul_f32_e32 v36, 0xbfb8aa3b, v42
	v_cndmask_b32_e64 v47, v40, v104, s[6:7]
	v_exp_f32_e32 v40, v36
	v_mov_b32_e32 v36, v41
	v_mov_b32_dpp v53, v41 row_ror:1 row_mask:0xf bank_mask:0xf
	v_mov_b32_dpp v54, v41 row_ror:2 row_mask:0xf bank_mask:0xf
	v_add_f32_e32 v40, 1.0, v40
	v_mul_f32_e32 v41, 0xbfb8aa3b, v34
	v_rcp_f32_e32 v40, v40
	v_exp_f32_e32 v41, v41
	v_cndmask_b32_e64 v44, v53, v73, s[8:9]
	v_pk_fma_f32 v[36:37], v[36:37], v[84:85], v[68:69]
	v_cndmask_b32_e64 v46, v54, v74, s[6:7]
	v_pk_fma_f32 v[36:37], v[82:83], v[44:45], v[36:37]
	v_mul_f32_e32 v40, v42, v40
	v_pk_fma_f32 v[36:37], v[80:81], v[46:47], v[36:37]
	v_add_f32_e32 v41, 1.0, v41
	v_mul_f32_e32 v42, 0xbfb8aa3b, v38
	v_mul_f32_e32 v40, v40, v43
	v_rcp_f32_e32 v41, v41
	v_exp_f32_e32 v42, v42
	v_mul_f32_e32 v43, 0xbfb8aa3b, v36
	v_exp_f32_e32 v43, v43
	v_mul_f32_e32 v34, v34, v41
	v_add_f32_e32 v41, 1.0, v42
	v_rcp_f32_e32 v41, v41
	v_add_f32_e32 v42, 1.0, v43
	v_rcp_f32_e32 v42, v42
	v_mul_f32_e32 v34, v34, v35
	v_mul_f32_e32 v35, v38, v41
	v_mul_f32_e32 v35, v35, v39
	v_mul_f32_e32 v36, v36, v42
	v_mul_f32_e32 v36, v36, v37
	v_cvt_pk_bf16_f32 v34, v40, v34
	v_cvt_pk_bf16_f32 v35, v35, v36
	v_mov_b32_e32 v160, v246
	v_mov_b32_e32 v161, v247
	v_mov_b32_e32 v162, v34
	v_mov_b32_e32 v163, v35
	global_store_dwordx4 v[124:125], v[160:163], off
	v_mov_b32_e32 v70, 0
	v_mov_b32_e32 v34, 0
	v_mov_b32_e32 v35, 0
	v_mov_b32_e32 v36, 0
	v_mov_b32_e32 v37, 0
	s_and_saveexec_b64 s[38:39], s[4:5]
	ds_read_b128 v[34:37], v218
	s_or_b64 exec, exec, s[38:39]
	v_mov_b32_e32 v71, 0
	v_mov_b32_e32 v72, 0
	v_mov_b32_e32 v73, 0
	s_and_saveexec_b64 s[38:39], s[4:5]
	ds_read_b128 v[70:73], v218 offset:512
	s_or_b64 exec, exec, s[38:39]
	s_waitcnt lgkmcnt(0)
	v_mov_b32_dpp v50, v36 row_ror:1 row_mask:0xf bank_mask:0xf
	v_mov_b32_dpp v52, v36 row_ror:2 row_mask:0xf bank_mask:0xf
	v_mov_b32_dpp v42, v30 row_ror:1 row_mask:0xf bank_mask:0xf
	v_mov_b32_dpp v40, v34 row_ror:1 row_mask:0xf bank_mask:0xf
	v_mov_b32_e32 v38, v30
	v_mov_b32_e32 v39, v26
	v_mov_b32_dpp v57, v26 row_ror:1 row_mask:0xf bank_mask:0xf
	v_mov_b32_dpp v36, v70 row_ror:1 row_mask:0xf bank_mask:0xf
	v_mov_b32_dpp v60, v26 row_ror:2 row_mask:0xf bank_mask:0xf
	v_mov_b32_dpp v43, v30 row_ror:2 row_mask:0xf bank_mask:0xf
	v_mov_b32_dpp v44, v34 row_ror:2 row_mask:0xf bank_mask:0xf
	v_mov_b32_dpp v54, v37 row_ror:1 row_mask:0xf bank_mask:0xf
	v_mov_b32_dpp v56, v37 row_ror:2 row_mask:0xf bank_mask:0xf
	v_mov_b32_dpp v26, v70 row_ror:2 row_mask:0xf bank_mask:0xf
	v_cndmask_b32_e64 v37, v57, v36, s[8:9]
	v_cndmask_b32_e64 v36, v42, v40, s[8:9]
	v_pk_fma_f32 v[38:39], v[38:39], v[76:77], v[78:79]
	v_cndmask_b32_e64 v41, v60, v26, s[6:7]
	v_cndmask_b32_e64 v40, v43, v44, s[6:7]
	v_pk_fma_f32 v[36:37], v[92:93], v[36:37], v[38:39]
	v_pk_fma_f32 v[36:37], v[94:95], v[40:41], v[36:37]
	v_mov_b32_dpp v45, v31 row_ror:1 row_mask:0xf bank_mask:0xf
	v_mov_b32_dpp v46, v35 row_ror:1 row_mask:0xf bank_mask:0xf
	v_mov_b32_dpp v47, v31 row_ror:2 row_mask:0xf bank_mask:0xf
	v_mov_b32_e32 v30, v31
	v_mov_b32_e32 v31, v27
	v_mov_b32_dpp v40, v27 row_ror:1 row_mask:0xf bank_mask:0xf
	v_mov_b32_dpp v26, v71 row_ror:1 row_mask:0xf bank_mask:0xf
	v_pk_fma_f32 v[30:31], v[30:31], v[90:91], v[66:67]
	v_mov_b32_dpp v41, v27 row_ror:2 row_mask:0xf bank_mask:0xf
	v_cndmask_b32_e64 v27, v40, v26, s[8:9]
	v_cndmask_b32_e64 v26, v45, v46, s[8:9]
	v_pk_fma_f32 v[26:27], v[88:89], v[26:27], v[30:31]
	v_mov_b32_dpp v48, v35 row_ror:2 row_mask:0xf bank_mask:0xf
	v_mov_b32_dpp v49, v32 row_ror:1 row_mask:0xf bank_mask:0xf
	v_mov_b32_e32 v34, v32
	v_mov_b32_e32 v35, v28
	v_mov_b32_dpp v38, v71 row_ror:2 row_mask:0xf bank_mask:0xf
	v_mov_b32_dpp v44, v28 row_ror:1 row_mask:0xf bank_mask:0xf
	v_mov_b32_dpp v30, v72 row_ror:1 row_mask:0xf bank_mask:0xf
	v_mov_b32_dpp v46, v28 row_ror:2 row_mask:0xf bank_mask:0xf
	v_mov_b32_dpp v51, v32 row_ror:2 row_mask:0xf bank_mask:0xf
	v_cndmask_b32_e64 v39, v41, v38, s[6:7]
	v_cndmask_b32_e64 v38, v47, v48, s[6:7]
	v_mov_b32_dpp v28, v72 row_ror:2 row_mask:0xf bank_mask:0xf
	v_cndmask_b32_e64 v31, v44, v30, s[8:9]
	v_cndmask_b32_e64 v30, v49, v50, s[8:9]
	v_pk_fma_f32 v[34:35], v[34:35], v[58:59], v[62:63]
	v_pk_fma_f32 v[26:27], v[86:87], v[38:39], v[26:27]
	v_cndmask_b32_e64 v39, v46, v28, s[6:7]
	v_cndmask_b32_e64 v38, v51, v52, s[6:7]
	v_pk_fma_f32 v[30:31], v[98:99], v[30:31], v[34:35]
	v_pk_fma_f32 v[30:31], v[102:103], v[38:39], v[30:31]
	v_mov_b32_dpp v53, v33 row_ror:1 row_mask:0xf bank_mask:0xf
	v_mov_b32_dpp v55, v33 row_ror:2 row_mask:0xf bank_mask:0xf
	v_mov_b32_e32 v32, v33
	v_mov_b32_e32 v33, v29
	v_mov_b32_dpp v38, v29 row_ror:1 row_mask:0xf bank_mask:0xf
	v_mov_b32_dpp v28, v73 row_ror:1 row_mask:0xf bank_mask:0xf
	v_pk_fma_f32 v[32:33], v[32:33], v[84:85], v[68:69]
	v_mov_b32_dpp v39, v29 row_ror:2 row_mask:0xf bank_mask:0xf
	v_cndmask_b32_e64 v29, v38, v28, s[8:9]
	v_cndmask_b32_e64 v28, v53, v54, s[8:9]
	v_pk_fma_f32 v[28:29], v[82:83], v[28:29], v[32:33]
	v_mul_f32_e32 v33, 0xbfb8aa3b, v26
	v_exp_f32_e32 v33, v33
	v_mov_b32_dpp v34, v73 row_ror:2 row_mask:0xf bank_mask:0xf
	v_cndmask_b32_e64 v35, v39, v34, s[6:7]
	v_mul_f32_e32 v34, 0xbfb8aa3b, v36
	v_exp_f32_e32 v48, v34
	v_cndmask_b32_e64 v34, v55, v56, s[6:7]
	v_pk_fma_f32 v[28:29], v[80:81], v[34:35], v[28:29]
	v_add_f32_e32 v33, 1.0, v33
	v_mul_f32_e32 v34, 0xbfb8aa3b, v30
	v_rcp_f32_e32 v33, v33
	v_exp_f32_e32 v34, v34
	v_mul_f32_e32 v35, 0xbfb8aa3b, v28
	v_exp_f32_e32 v35, v35
	v_mul_f32_e32 v26, v26, v33
	v_add_f32_e32 v33, 1.0, v34
	v_add_f32_e32 v32, 1.0, v48
	v_rcp_f32_e32 v33, v33
	v_add_f32_e32 v34, 1.0, v35
	v_rcp_f32_e32 v32, v32
	v_rcp_f32_e32 v34, v34
	v_mul_f32_e32 v26, v26, v27
	v_mul_f32_e32 v27, v30, v33
	v_mul_f32_e32 v32, v36, v32
	v_mul_f32_e32 v27, v27, v31
	v_mul_f32_e32 v28, v28, v34
	v_mul_f32_e32 v32, v32, v37
	v_mul_f32_e32 v28, v28, v29
	v_cvt_pk_bf16_f32 v26, v32, v26
	v_cvt_pk_bf16_f32 v27, v27, v28
	v_mov_b32_e32 v164, v248
	v_mov_b32_e32 v165, v249
	v_mov_b32_e32 v166, v26
	v_mov_b32_e32 v167, v27
	global_store_dwordx4 v[96:97], v[164:167], off
	v_mov_b32_dpp v34, v22 row_ror:1 row_mask:0xf bank_mask:0xf
	v_mov_b32_e32 v26, v22
	v_mov_b32_e32 v27, v18
	v_mov_b32_dpp v56, v18 row_ror:1 row_mask:0xf bank_mask:0xf
	v_mov_b32_dpp v35, v22 row_ror:2 row_mask:0xf bank_mask:0xf
	v_cndmask_b32_e64 v31, v56, v57, s[8:9]
	v_mov_b32_dpp v61, v18 row_ror:2 row_mask:0xf bank_mask:0xf
	v_cndmask_b32_e64 v30, v34, v42, s[8:9]
	v_pk_fma_f32 v[26:27], v[26:27], v[76:77], v[78:79]
	v_cndmask_b32_e64 v33, v61, v60, s[6:7]
	v_cndmask_b32_e64 v32, v35, v43, s[6:7]
	v_pk_fma_f32 v[26:27], v[92:93], v[30:31], v[26:27]
	v_pk_fma_f32 v[26:27], v[94:95], v[32:33], v[26:27]
	v_mov_b32_dpp v32, v19 row_ror:1 row_mask:0xf bank_mask:0xf
	v_mov_b32_dpp v36, v23 row_ror:1 row_mask:0xf bank_mask:0xf
	v_mov_b32_dpp v37, v23 row_ror:2 row_mask:0xf bank_mask:0xf
	v_mov_b32_e32 v22, v23
	v_mov_b32_e32 v23, v19
	v_mov_b32_dpp v33, v19 row_ror:2 row_mask:0xf bank_mask:0xf
	v_cndmask_b32_e64 v19, v32, v40, s[8:9]
	v_mov_b32_dpp v48, v24 row_ror:1 row_mask:0xf bank_mask:0xf
	v_mov_b32_e32 v28, v24
	v_mov_b32_e32 v29, v20
	v_cndmask_b32_e64 v18, v36, v45, s[8:9]
	v_cndmask_b32_e64 v31, v33, v41, s[6:7]
	v_pk_fma_f32 v[22:23], v[22:23], v[90:91], v[66:67]
	v_mov_b32_dpp v40, v20 row_ror:1 row_mask:0xf bank_mask:0xf
	v_mov_b32_dpp v50, v24 row_ror:2 row_mask:0xf bank_mask:0xf
	v_cndmask_b32_e64 v30, v37, v47, s[6:7]
	v_pk_fma_f32 v[18:19], v[88:89], v[18:19], v[22:23]
	v_mov_b32_dpp v41, v20 row_ror:2 row_mask:0xf bank_mask:0xf
	v_cndmask_b32_e64 v23, v40, v44, s[8:9]
	v_cndmask_b32_e64 v22, v48, v49, s[8:9]
	v_pk_fma_f32 v[28:29], v[28:29], v[58:59], v[62:63]
	v_pk_fma_f32 v[18:19], v[86:87], v[30:31], v[18:19]
	v_cndmask_b32_e64 v31, v41, v46, s[6:7]
	v_cndmask_b32_e64 v30, v50, v51, s[6:7]
	v_pk_fma_f32 v[22:23], v[98:99], v[22:23], v[28:29]
	v_pk_fma_f32 v[22:23], v[102:103], v[30:31], v[22:23]
	v_mov_b32_dpp v30, v21 row_ror:1 row_mask:0xf bank_mask:0xf
	v_mul_f32_e32 v28, 0xbfb8aa3b, v26
	v_mov_b32_dpp v52, v25 row_ror:1 row_mask:0xf bank_mask:0xf
	v_mov_b32_dpp v54, v25 row_ror:2 row_mask:0xf bank_mask:0xf
	v_mov_b32_e32 v24, v25
	v_mov_b32_e32 v25, v21
	v_mov_b32_dpp v31, v21 row_ror:2 row_mask:0xf bank_mask:0xf
	v_cndmask_b32_e64 v21, v30, v38, s[8:9]
	v_exp_f32_e32 v38, v28
	v_cndmask_b32_e64 v20, v52, v53, s[8:9]
	v_pk_fma_f32 v[24:25], v[24:25], v[84:85], v[68:69]
	v_cndmask_b32_e64 v29, v31, v39, s[6:7]
	v_pk_fma_f32 v[20:21], v[82:83], v[20:21], v[24:25]
	v_add_f32_e32 v24, 1.0, v38
	v_mul_f32_e32 v25, 0xbfb8aa3b, v18
	v_rcp_f32_e32 v24, v24
	v_exp_f32_e32 v25, v25
	v_cndmask_b32_e64 v28, v54, v55, s[6:7]
	v_pk_fma_f32 v[20:21], v[80:81], v[28:29], v[20:21]
	v_mul_f32_e32 v24, v26, v24
	v_add_f32_e32 v25, 1.0, v25
	v_mul_f32_e32 v26, 0xbfb8aa3b, v22
	v_mul_f32_e32 v24, v24, v27
	v_rcp_f32_e32 v25, v25
	v_exp_f32_e32 v26, v26
	v_mul_f32_e32 v27, 0xbfb8aa3b, v20
	v_exp_f32_e32 v27, v27
	v_mul_f32_e32 v18, v18, v25
	v_add_f32_e32 v25, 1.0, v26
	v_rcp_f32_e32 v25, v25
	v_add_f32_e32 v26, 1.0, v27
	v_rcp_f32_e32 v26, v26
	v_mul_f32_e32 v18, v18, v19
	v_mul_f32_e32 v19, v22, v25
	v_mul_f32_e32 v19, v19, v23
	v_mul_f32_e32 v20, v20, v26
	v_mul_f32_e32 v20, v20, v21
	v_cvt_pk_bf16_f32 v18, v24, v18
	v_cvt_pk_bf16_f32 v19, v19, v20
	v_mov_b32_e32 v168, v250
	v_mov_b32_e32 v169, v251
	v_mov_b32_e32 v170, v18
	v_mov_b32_e32 v171, v19
	global_store_dwordx4 v[126:127], v[168:171], off
	v_mov_b32_dpp v26, v14 row_ror:1 row_mask:0xf bank_mask:0xf
	v_mov_b32_e32 v18, v14
	v_mov_b32_e32 v19, v10
	v_mov_b32_dpp v44, v10 row_ror:1 row_mask:0xf bank_mask:0xf
	v_mov_b32_dpp v27, v14 row_ror:2 row_mask:0xf bank_mask:0xf
	v_cndmask_b32_e64 v23, v44, v56, s[8:9]
	v_mov_b32_dpp v45, v10 row_ror:2 row_mask:0xf bank_mask:0xf
	v_cndmask_b32_e64 v22, v26, v34, s[8:9]
	v_pk_fma_f32 v[18:19], v[18:19], v[76:77], v[78:79]
	v_cndmask_b32_e64 v25, v45, v61, s[6:7]
	v_cndmask_b32_e64 v24, v27, v35, s[6:7]
	v_pk_fma_f32 v[18:19], v[92:93], v[22:23], v[18:19]
	v_pk_fma_f32 v[18:19], v[94:95], v[24:25], v[18:19]
	v_mov_b32_dpp v24, v11 row_ror:1 row_mask:0xf bank_mask:0xf
	v_mov_b32_dpp v28, v15 row_ror:1 row_mask:0xf bank_mask:0xf
	v_mov_b32_dpp v29, v15 row_ror:2 row_mask:0xf bank_mask:0xf
	v_mov_b32_e32 v14, v15
	v_mov_b32_e32 v15, v11
	v_mov_b32_dpp v25, v11 row_ror:2 row_mask:0xf bank_mask:0xf
	v_cndmask_b32_e64 v11, v24, v32, s[8:9]
	v_mov_b32_dpp v38, v16 row_ror:1 row_mask:0xf bank_mask:0xf
	v_mov_b32_e32 v20, v16
	v_mov_b32_e32 v21, v12
	v_cndmask_b32_e64 v10, v28, v36, s[8:9]
	v_cndmask_b32_e64 v23, v25, v33, s[6:7]
	v_pk_fma_f32 v[14:15], v[14:15], v[90:91], v[66:67]
	v_mov_b32_dpp v32, v12 row_ror:1 row_mask:0xf bank_mask:0xf
	v_mov_b32_dpp v39, v16 row_ror:2 row_mask:0xf bank_mask:0xf
	v_cndmask_b32_e64 v22, v29, v37, s[6:7]
	v_pk_fma_f32 v[10:11], v[88:89], v[10:11], v[14:15]
	v_mov_b32_dpp v33, v12 row_ror:2 row_mask:0xf bank_mask:0xf
	v_cndmask_b32_e64 v15, v32, v40, s[8:9]
	v_cndmask_b32_e64 v14, v38, v48, s[8:9]
	v_pk_fma_f32 v[20:21], v[20:21], v[58:59], v[62:63]
	v_pk_fma_f32 v[10:11], v[86:87], v[22:23], v[10:11]
	v_cndmask_b32_e64 v23, v33, v41, s[6:7]
	v_cndmask_b32_e64 v22, v39, v50, s[6:7]
	v_pk_fma_f32 v[14:15], v[98:99], v[14:15], v[20:21]
	v_pk_fma_f32 v[14:15], v[102:103], v[22:23], v[14:15]
	v_mov_b32_dpp v22, v13 row_ror:1 row_mask:0xf bank_mask:0xf
	v_mul_f32_e32 v20, 0xbfb8aa3b, v18
	v_mov_b32_dpp v42, v17 row_ror:1 row_mask:0xf bank_mask:0xf
	v_mov_b32_dpp v43, v17 row_ror:2 row_mask:0xf bank_mask:0xf
	v_mov_b32_e32 v16, v17
	v_mov_b32_e32 v17, v13
	v_mov_b32_dpp v23, v13 row_ror:2 row_mask:0xf bank_mask:0xf
	v_cndmask_b32_e64 v13, v22, v30, s[8:9]
	v_exp_f32_e32 v30, v20
	v_cndmask_b32_e64 v12, v42, v52, s[8:9]
	v_pk_fma_f32 v[16:17], v[16:17], v[84:85], v[68:69]
	v_cndmask_b32_e64 v21, v23, v31, s[6:7]
	v_pk_fma_f32 v[12:13], v[82:83], v[12:13], v[16:17]
	v_add_f32_e32 v16, 1.0, v30
	v_mul_f32_e32 v17, 0xbfb8aa3b, v10
	v_rcp_f32_e32 v16, v16
	v_exp_f32_e32 v17, v17
	v_cndmask_b32_e64 v20, v43, v54, s[6:7]
	v_pk_fma_f32 v[12:13], v[80:81], v[20:21], v[12:13]
	v_mul_f32_e32 v16, v18, v16
	v_add_f32_e32 v17, 1.0, v17
	v_mul_f32_e32 v18, 0xbfb8aa3b, v14
	v_mul_f32_e32 v16, v16, v19
	v_rcp_f32_e32 v17, v17
	v_exp_f32_e32 v18, v18
	v_mul_f32_e32 v19, 0xbfb8aa3b, v12
	v_exp_f32_e32 v19, v19
	v_mul_f32_e32 v10, v10, v17
	v_add_f32_e32 v17, 1.0, v18
	v_rcp_f32_e32 v17, v17
	v_add_f32_e32 v18, 1.0, v19
	v_rcp_f32_e32 v18, v18
	v_mul_f32_e32 v10, v10, v11
	v_mul_f32_e32 v11, v14, v17
	v_mul_f32_e32 v11, v11, v15
	v_mul_f32_e32 v12, v12, v18
	v_mul_f32_e32 v12, v12, v13
	v_cvt_pk_bf16_f32 v10, v16, v10
	v_cvt_pk_bf16_f32 v11, v11, v12
	v_mov_b32_e32 v172, v252
	v_mov_b32_e32 v173, v253
	v_mov_b32_e32 v174, v10
	v_mov_b32_e32 v175, v11
	global_store_dwordx4 v[128:129], v[172:175], off
	v_mov_b32_dpp v14, v6 row_ror:1 row_mask:0xf bank_mask:0xf
	v_mov_b32_e32 v10, v6
	v_mov_b32_e32 v11, v2
	v_mov_b32_dpp v15, v2 row_ror:1 row_mask:0xf bank_mask:0xf
	v_mov_b32_dpp v17, v2 row_ror:2 row_mask:0xf bank_mask:0xf
	v_cndmask_b32_e64 v15, v15, v44, s[8:9]
	v_cndmask_b32_e64 v14, v14, v26, s[8:9]
	v_pk_fma_f32 v[10:11], v[10:11], v[76:77], v[78:79]
	v_mov_b32_dpp v16, v6 row_ror:2 row_mask:0xf bank_mask:0xf
	v_mov_b32_dpp v18, v7 row_ror:1 row_mask:0xf bank_mask:0xf
	v_mov_b32_dpp v19, v7 row_ror:2 row_mask:0xf bank_mask:0xf
	v_mov_b32_e32 v6, v7
	v_mov_b32_e32 v7, v3
	v_pk_fma_f32 v[10:11], v[92:93], v[14:15], v[10:11]
	v_mov_b32_dpp v2, v3 row_ror:1 row_mask:0xf bank_mask:0xf
	v_pk_fma_f32 v[6:7], v[6:7], v[90:91], v[66:67]
	v_mov_b32_dpp v14, v3 row_ror:2 row_mask:0xf bank_mask:0xf
	v_cndmask_b32_e64 v3, v2, v24, s[8:9]
	v_cndmask_b32_e64 v2, v18, v28, s[8:9]
	v_pk_fma_f32 v[2:3], v[88:89], v[2:3], v[6:7]
	v_mov_b32_dpp v20, v8 row_ror:1 row_mask:0xf bank_mask:0xf
	v_mov_b32_e32 v12, v8
	v_mov_b32_e32 v13, v4
	v_mov_b32_dpp v6, v4 row_ror:1 row_mask:0xf bank_mask:0xf
	v_cndmask_b32_e64 v15, v14, v25, s[6:7]
	v_cndmask_b32_e64 v14, v19, v29, s[6:7]
	v_cndmask_b32_e64 v7, v6, v32, s[8:9]
	v_cndmask_b32_e64 v6, v20, v38, s[8:9]
	v_pk_fma_f32 v[12:13], v[12:13], v[58:59], v[62:63]
	v_cndmask_b32_e64 v17, v17, v45, s[6:7]
	v_cndmask_b32_e64 v16, v16, v27, s[6:7]
	v_pk_fma_f32 v[2:3], v[86:87], v[14:15], v[2:3]
	v_pk_fma_f32 v[6:7], v[98:99], v[6:7], v[12:13]
	v_mov_b32_dpp v21, v8 row_ror:2 row_mask:0xf bank_mask:0xf
	v_pk_fma_f32 v[10:11], v[94:95], v[16:17], v[10:11]
	v_mov_b32_dpp v14, v4 row_ror:2 row_mask:0xf bank_mask:0xf
	v_mov_b32_dpp v12, v5 row_ror:2 row_mask:0xf bank_mask:0xf
	v_cndmask_b32_e64 v15, v14, v33, s[6:7]
	v_cndmask_b32_e64 v14, v21, v39, s[6:7]
	v_cndmask_b32_e64 v13, v12, v23, s[6:7]
	v_mul_f32_e32 v12, 0xbfb8aa3b, v10
	v_pk_fma_f32 v[6:7], v[102:103], v[14:15], v[6:7]
	v_exp_f32_e32 v14, v12
	v_mov_b32_dpp v30, v9 row_ror:1 row_mask:0xf bank_mask:0xf
	v_mov_b32_dpp v31, v9 row_ror:2 row_mask:0xf bank_mask:0xf
	v_mov_b32_e32 v8, v9
	v_mov_b32_e32 v9, v5
	v_mov_b32_dpp v4, v5 row_ror:1 row_mask:0xf bank_mask:0xf
	v_cndmask_b32_e64 v5, v4, v22, s[8:9]
	v_cndmask_b32_e64 v4, v30, v42, s[8:9]
	v_pk_fma_f32 v[8:9], v[8:9], v[84:85], v[68:69]
	v_cndmask_b32_e64 v12, v31, v43, s[6:7]
	v_pk_fma_f32 v[4:5], v[82:83], v[4:5], v[8:9]
	v_add_f32_e32 v8, 1.0, v14
	v_mul_f32_e32 v9, 0xbfb8aa3b, v2
	v_rcp_f32_e32 v8, v8
	v_exp_f32_e32 v9, v9
	v_pk_fma_f32 v[4:5], v[80:81], v[12:13], v[4:5]
	s_andn2_b64 vcc, exec, s[10:11]
	v_mul_f32_e32 v8, v10, v8
	v_add_f32_e32 v9, 1.0, v9
	v_mul_f32_e32 v10, 0xbfb8aa3b, v6
	v_mul_f32_e32 v8, v8, v11
	v_rcp_f32_e32 v9, v9
	v_exp_f32_e32 v10, v10
	v_mul_f32_e32 v11, 0xbfb8aa3b, v4
	v_exp_f32_e32 v11, v11
	v_mul_f32_e32 v2, v2, v9
	v_add_f32_e32 v9, 1.0, v10
	v_rcp_f32_e32 v9, v9
	v_add_f32_e32 v10, 1.0, v11
	v_rcp_f32_e32 v10, v10
	v_mul_f32_e32 v2, v2, v3
	v_mul_f32_e32 v3, v6, v9
	v_mul_f32_e32 v3, v3, v7
	v_mul_f32_e32 v4, v4, v10
	v_mul_f32_e32 v4, v4, v5
	v_cvt_pk_bf16_f32 v2, v8, v2
	v_cvt_pk_bf16_f32 v3, v3, v4
	v_mov_b32_e32 v176, v230
	v_mov_b32_e32 v177, v231
	v_mov_b32_e32 v178, v2
	v_mov_b32_e32 v179, v3
	global_store_dwordx4 v[130:131], v[176:179], off
	s_mov_b64 s[10:11], -1
	s_cbranch_vccnz .LBB0_1868
	s_andn2_b64 vcc, exec, s[0:1]
	s_cbranch_vccnz .LBB0_1867
	s_barrier
	s_branch .LBB0_1867
